# v58 + diff_finish2 row stores: one 64-bit address per row (dedicated pair) with offset:64/128/192 instead of rebuilding the address for each of the four stores
# baseline (speedup 1.0000x reference)
.LBB0_1174:
	s_or_b64 exec, exec, s[4:5]
	s_waitcnt lgkmcnt(0)
	v_lshlrev_b32_e32 v2, 2, v158
	global_load_dword v249, v2, s[0:1]
	global_load_dword v250, v2, s[0:1] offset:128
	global_load_dword v251, v2, s[0:1] offset:256
	global_load_dword v253, v2, s[0:1] offset:384
	v_add_u32_e32 v10, s19, v148
	s_lshl_b64 s[4:5], s[10:11], 13
	s_add_u32 s4, s86, s4
	s_addc_u32 s5, s87, s5
	s_add_u32 s6, s4, s46
	s_addc_u32 s7, s5, 0
	s_waitcnt vmcnt(0)
	v_mul_f32_e32 v7, v164, v249
	v_mul_f32_e32 v9, v164, v250
	v_mul_f32_e32 v6, v164, v251
	v_mul_f32_e32 v8, v164, v253
	v_lshl_or_b32 v2, v159, 14, v158
	ds_read_b32 v11, v10
	ds_read2st64_b32 v[4:5], v1 offset1:16
	ds_read_b32 v23, v10 offset:4
	ds_read2st64_b32 v[16:17], v1 offset0:1 offset1:17
	s_waitcnt lgkmcnt(0)
	v_fma_f32 v12, v84, v11, -v4
	v_fma_f32 v13, v100, v11, -v5
	ds_read2st64_b32 v[4:5], v1 offset0:32 offset1:48
	v_mul_f32_e32 v14, v13, v13
	v_fmac_f32_e32 v14, v12, v12
	v_fma_f32 v24, v85, v23, -v16
	v_fma_f32 v25, v101, v23, -v17
	ds_read2st64_b32 v[16:17], v1 offset0:33 offset1:49
	v_mul_f32_e32 v26, v25, v25
	v_fmac_f32_e32 v26, v24, v24
	s_waitcnt lgkmcnt(0)
	v_fma_f32 v15, v116, v11, -v4
	v_fmac_f32_e32 v14, v15, v15
	v_fma_f32 v11, v132, v11, -v5
	v_fmac_f32_e32 v14, v11, v11
	s_nop 1
	v_add_f32_dpp v4, v14, v14 quad_perm:[1,0,3,2] row_mask:0xf bank_mask:0xf
	s_nop 1
	v_add_f32_dpp v4, v4, v4 quad_perm:[2,3,0,1] row_mask:0xf bank_mask:0xf
	s_nop 1
	v_add_f32_dpp v4, v4, v4 row_half_mirror row_mask:0xf bank_mask:0xf
	s_nop 1
	v_add_f32_dpp v4, v4, v4 row_mirror row_mask:0xf bank_mask:0xf
	ds_swizzle_b32 v5, v4 offset:swizzle(SWAP,16)
	v_fma_f32 v27, v117, v23, -v16
	v_fmac_f32_e32 v26, v27, v27
	v_fma_f32 v23, v133, v23, -v17
	v_fmac_f32_e32 v26, v23, v23
	s_nop 1
	v_add_f32_dpp v16, v26, v26 quad_perm:[1,0,3,2] row_mask:0xf bank_mask:0xf
	s_nop 1
	v_add_f32_dpp v16, v16, v16 quad_perm:[2,3,0,1] row_mask:0xf bank_mask:0xf
	s_nop 1
	v_add_f32_dpp v16, v16, v16 row_half_mirror row_mask:0xf bank_mask:0xf
	s_nop 1
	v_add_f32_dpp v16, v16, v16 row_mirror row_mask:0xf bank_mask:0xf
	ds_swizzle_b32 v17, v16 offset:swizzle(SWAP,16)
	s_waitcnt lgkmcnt(0)
	v_add_f32_e32 v4, v4, v5
	v_fmamk_f32 v4, v4, 0x3c000000, v254
	s_nop 0
	s_nop 0
	s_nop 0
	s_nop 1
	s_nop 1
	s_nop 0
	v_rsq_f32_e32 v14, v4
	s_nop 0
	v_mul_f32_e32 v4, v12, v14
	v_mul_f32_e32 v5, v13, v14
	v_mul_f32_e32 v4, v7, v4
	v_mul_f32_e32 v5, v9, v5
	v_cvt_pk_bf16_f32 v12, v4, v5
	v_lshl_add_u64 v[4:5], v[2:3], 1, s[6:7]
	global_store_short v[4:5], v12, off
	v_add_u32_e32 v4, 32, v2
	v_mov_b32_e32 v5, v3
	v_lshl_add_u64 v[4:5], v[4:5], 1, s[6:7]
	global_store_short_d16_hi v[4:5], v12, off
	v_mul_f32_e32 v4, v15, v14
	v_mul_f32_e32 v5, v11, v14
	v_mul_f32_e32 v4, v6, v4
	v_mul_f32_e32 v5, v8, v5
	v_cvt_pk_bf16_f32 v11, v4, v5
	v_add_u32_e32 v4, 64, v2
	v_mov_b32_e32 v5, v3
	v_lshl_add_u64 v[4:5], v[4:5], 1, s[6:7]
	global_store_short v[4:5], v11, off
	v_add_u32_e32 v4, 0x60, v2
	v_mov_b32_e32 v5, v3
	v_lshl_add_u64 v[4:5], v[4:5], 1, s[6:7]
	global_store_short_d16_hi v[4:5], v11, off
	v_add_f32_e32 v16, v16, v17
	v_fmamk_f32 v16, v16, 0x3c000000, v254
	s_nop 0
	s_nop 0
	s_nop 0
	s_nop 1
	s_nop 1
	s_nop 0
	v_rsq_f32_e32 v26, v16
	s_nop 0
	v_mul_f32_e32 v17, v24, v26
	v_mul_f32_e32 v24, v25, v26
	v_mul_f32_e32 v17, v7, v17
	v_mul_f32_e32 v24, v9, v24
	v_add_u32_e32 v20, 0x1000, v2
	v_cvt_pk_bf16_f32 v24, v17, v24
	v_mov_b32_e32 v21, v3
	v_lshl_add_u64 v[20:21], v[20:21], 1, s[6:7]
	global_store_short v[20:21], v24, off
	global_store_short_d16_hi v[20:21], v24, off offset:64
	v_mul_f32_e32 v16, v27, v26
	v_mul_f32_e32 v17, v23, v26
	v_mul_f32_e32 v16, v6, v16
	v_mul_f32_e32 v17, v8, v17
	v_cvt_pk_bf16_f32 v23, v16, v17
	global_store_short v[20:21], v23, off offset:128
	global_store_short_d16_hi v[20:21], v23, off offset:192
	ds_read_b32 v11, v10 offset:8
	ds_read2st64_b32 v[4:5], v1 offset0:2 offset1:18
	ds_read_b32 v23, v10 offset:12
	ds_read2st64_b32 v[16:17], v1 offset0:3 offset1:19
	s_waitcnt lgkmcnt(0)
	v_fma_f32 v12, v86, v11, -v4
	v_fma_f32 v13, v102, v11, -v5
	ds_read2st64_b32 v[4:5], v1 offset0:34 offset1:50
	v_mul_f32_e32 v14, v13, v13
	v_fmac_f32_e32 v14, v12, v12
	v_fma_f32 v24, v87, v23, -v16
	v_fma_f32 v25, v103, v23, -v17
	ds_read2st64_b32 v[16:17], v1 offset0:35 offset1:51
	v_mul_f32_e32 v26, v25, v25
	v_fmac_f32_e32 v26, v24, v24
	s_waitcnt lgkmcnt(0)
	v_fma_f32 v15, v118, v11, -v4
	v_fmac_f32_e32 v14, v15, v15
	v_fma_f32 v11, v134, v11, -v5
	v_fmac_f32_e32 v14, v11, v11
	s_nop 1
	v_add_f32_dpp v4, v14, v14 quad_perm:[1,0,3,2] row_mask:0xf bank_mask:0xf
	s_nop 1
	v_add_f32_dpp v4, v4, v4 quad_perm:[2,3,0,1] row_mask:0xf bank_mask:0xf
	s_nop 1
	v_add_f32_dpp v4, v4, v4 row_half_mirror row_mask:0xf bank_mask:0xf
	s_nop 1
	v_add_f32_dpp v4, v4, v4 row_mirror row_mask:0xf bank_mask:0xf
	ds_swizzle_b32 v5, v4 offset:swizzle(SWAP,16)
	v_fma_f32 v27, v119, v23, -v16
	v_fmac_f32_e32 v26, v27, v27
	v_fma_f32 v23, v135, v23, -v17
	v_fmac_f32_e32 v26, v23, v23
	s_nop 1
	v_add_f32_dpp v16, v26, v26 quad_perm:[1,0,3,2] row_mask:0xf bank_mask:0xf
	s_nop 1
	v_add_f32_dpp v16, v16, v16 quad_perm:[2,3,0,1] row_mask:0xf bank_mask:0xf
	s_nop 1
	v_add_f32_dpp v16, v16, v16 row_half_mirror row_mask:0xf bank_mask:0xf
	s_nop 1
	v_add_f32_dpp v16, v16, v16 row_mirror row_mask:0xf bank_mask:0xf
	ds_swizzle_b32 v17, v16 offset:swizzle(SWAP,16)
	s_waitcnt lgkmcnt(0)
	v_add_f32_e32 v4, v4, v5
	v_fmamk_f32 v4, v4, 0x3c000000, v254
	s_nop 0
	s_nop 0
	s_nop 0
	s_nop 1
	s_nop 1
	s_nop 0
	v_rsq_f32_e32 v14, v4
	s_nop 0
	v_mul_f32_e32 v5, v12, v14
	v_mul_f32_e32 v12, v13, v14
	v_mul_f32_e32 v5, v7, v5
	v_mul_f32_e32 v12, v9, v12
	v_add_u32_e32 v18, 0x2000, v2
	v_cvt_pk_bf16_f32 v12, v5, v12
	v_mov_b32_e32 v19, v3
	v_lshl_add_u64 v[18:19], v[18:19], 1, s[6:7]
	global_store_short v[18:19], v12, off
	global_store_short_d16_hi v[18:19], v12, off offset:64
	v_mul_f32_e32 v4, v15, v14
	v_mul_f32_e32 v5, v11, v14
	v_mul_f32_e32 v4, v6, v4
	v_mul_f32_e32 v5, v8, v5
	v_cvt_pk_bf16_f32 v11, v4, v5
	global_store_short v[18:19], v11, off offset:128
	global_store_short_d16_hi v[18:19], v11, off offset:192
	v_add_f32_e32 v16, v16, v17
	v_fmamk_f32 v16, v16, 0x3c000000, v254
	s_nop 0
	s_nop 0
	s_nop 0
	s_nop 1
	s_nop 1
	s_nop 0
	v_rsq_f32_e32 v26, v16
	s_nop 0
	v_mul_f32_e32 v17, v24, v26
	v_mul_f32_e32 v24, v25, v26
	v_mul_f32_e32 v17, v7, v17
	v_mul_f32_e32 v24, v9, v24
	v_add_u32_e32 v20, 0x3000, v2
	v_cvt_pk_bf16_f32 v24, v17, v24
	v_mov_b32_e32 v21, v3
	v_lshl_add_u64 v[20:21], v[20:21], 1, s[6:7]
	global_store_short v[20:21], v24, off
	global_store_short_d16_hi v[20:21], v24, off offset:64
	v_mul_f32_e32 v16, v27, v26
	v_mul_f32_e32 v17, v23, v26
	v_mul_f32_e32 v16, v6, v16
	v_mul_f32_e32 v17, v8, v17
	v_cvt_pk_bf16_f32 v23, v16, v17
	global_store_short v[20:21], v23, off offset:128
	global_store_short_d16_hi v[20:21], v23, off offset:192
	ds_read_b32 v11, v10 offset:32
	ds_read2st64_b32 v[4:5], v1 offset0:4 offset1:20
	ds_read_b32 v23, v10 offset:36
	ds_read2st64_b32 v[16:17], v1 offset0:5 offset1:21
	s_waitcnt lgkmcnt(0)
	v_fma_f32 v12, v88, v11, -v4
	v_fma_f32 v13, v104, v11, -v5
	ds_read2st64_b32 v[4:5], v1 offset0:36 offset1:52
	v_mul_f32_e32 v14, v13, v13
	v_fmac_f32_e32 v14, v12, v12
	v_fma_f32 v24, v89, v23, -v16
	v_fma_f32 v25, v105, v23, -v17
	ds_read2st64_b32 v[16:17], v1 offset0:37 offset1:53
	v_mul_f32_e32 v26, v25, v25
	v_fmac_f32_e32 v26, v24, v24
	s_waitcnt lgkmcnt(0)
	v_fma_f32 v15, v120, v11, -v4
	v_fmac_f32_e32 v14, v15, v15
	v_fma_f32 v11, v136, v11, -v5
	v_fmac_f32_e32 v14, v11, v11
	s_nop 1
	v_add_f32_dpp v4, v14, v14 quad_perm:[1,0,3,2] row_mask:0xf bank_mask:0xf
	s_nop 1
	v_add_f32_dpp v4, v4, v4 quad_perm:[2,3,0,1] row_mask:0xf bank_mask:0xf
	s_nop 1
	v_add_f32_dpp v4, v4, v4 row_half_mirror row_mask:0xf bank_mask:0xf
	s_nop 1
	v_add_f32_dpp v4, v4, v4 row_mirror row_mask:0xf bank_mask:0xf
	ds_swizzle_b32 v5, v4 offset:swizzle(SWAP,16)
	v_fma_f32 v27, v121, v23, -v16
	v_fmac_f32_e32 v26, v27, v27
	v_fma_f32 v23, v137, v23, -v17
	v_fmac_f32_e32 v26, v23, v23
	s_nop 1
	v_add_f32_dpp v16, v26, v26 quad_perm:[1,0,3,2] row_mask:0xf bank_mask:0xf
	s_nop 1
	v_add_f32_dpp v16, v16, v16 quad_perm:[2,3,0,1] row_mask:0xf bank_mask:0xf
	s_nop 1
	v_add_f32_dpp v16, v16, v16 row_half_mirror row_mask:0xf bank_mask:0xf
	s_nop 1
	v_add_f32_dpp v16, v16, v16 row_mirror row_mask:0xf bank_mask:0xf
	ds_swizzle_b32 v17, v16 offset:swizzle(SWAP,16)
	s_waitcnt lgkmcnt(0)
	v_add_f32_e32 v4, v4, v5
	v_fmamk_f32 v4, v4, 0x3c000000, v254
	s_nop 0
	s_nop 0
	s_nop 0
	s_nop 1
	s_nop 1
	s_nop 0
	v_rsq_f32_e32 v14, v4
	s_nop 0
	v_mul_f32_e32 v5, v12, v14
	v_mul_f32_e32 v12, v13, v14
	v_mul_f32_e32 v5, v7, v5
	v_mul_f32_e32 v12, v9, v12
	v_add_u32_e32 v18, 0x8000, v2
	v_cvt_pk_bf16_f32 v12, v5, v12
	v_mov_b32_e32 v19, v3
	v_lshl_add_u64 v[18:19], v[18:19], 1, s[6:7]
	global_store_short v[18:19], v12, off
	global_store_short_d16_hi v[18:19], v12, off offset:64
	v_mul_f32_e32 v4, v15, v14
	v_mul_f32_e32 v5, v11, v14
	v_mul_f32_e32 v4, v6, v4
	v_mul_f32_e32 v5, v8, v5
	v_cvt_pk_bf16_f32 v11, v4, v5
	global_store_short v[18:19], v11, off offset:128
	global_store_short_d16_hi v[18:19], v11, off offset:192
	v_add_f32_e32 v16, v16, v17
	v_fmamk_f32 v16, v16, 0x3c000000, v254
	s_nop 0
	s_nop 0
	s_nop 0
	s_nop 1
	s_nop 1
	s_nop 0
	v_rsq_f32_e32 v26, v16
	s_nop 0
	v_mul_f32_e32 v17, v24, v26
	v_mul_f32_e32 v24, v25, v26
	v_mul_f32_e32 v17, v7, v17
	v_mul_f32_e32 v24, v9, v24
	v_add_u32_e32 v20, 0x9000, v2
	v_cvt_pk_bf16_f32 v24, v17, v24
	v_mov_b32_e32 v21, v3
	v_lshl_add_u64 v[20:21], v[20:21], 1, s[6:7]
	global_store_short v[20:21], v24, off
	global_store_short_d16_hi v[20:21], v24, off offset:64
	v_mul_f32_e32 v16, v27, v26
	v_mul_f32_e32 v17, v23, v26
	v_mul_f32_e32 v16, v6, v16
	v_mul_f32_e32 v17, v8, v17
	v_cvt_pk_bf16_f32 v23, v16, v17
	global_store_short v[20:21], v23, off offset:128
	global_store_short_d16_hi v[20:21], v23, off offset:192
	ds_read_b32 v11, v10 offset:40
	ds_read2st64_b32 v[4:5], v1 offset0:6 offset1:22
	ds_read_b32 v23, v10 offset:44
	ds_read2st64_b32 v[16:17], v1 offset0:7 offset1:23
	s_waitcnt lgkmcnt(0)
	v_fma_f32 v12, v90, v11, -v4
	v_fma_f32 v13, v106, v11, -v5
	ds_read2st64_b32 v[4:5], v1 offset0:38 offset1:54
	v_mul_f32_e32 v14, v13, v13
	v_fmac_f32_e32 v14, v12, v12
	v_fma_f32 v24, v91, v23, -v16
	v_fma_f32 v25, v107, v23, -v17
	ds_read2st64_b32 v[16:17], v1 offset0:39 offset1:55
	v_mul_f32_e32 v26, v25, v25
	v_fmac_f32_e32 v26, v24, v24
	s_waitcnt lgkmcnt(0)
	v_fma_f32 v15, v122, v11, -v4
	v_fmac_f32_e32 v14, v15, v15
	v_fma_f32 v11, v138, v11, -v5
	v_fmac_f32_e32 v14, v11, v11
	s_nop 1
	v_add_f32_dpp v4, v14, v14 quad_perm:[1,0,3,2] row_mask:0xf bank_mask:0xf
	s_nop 1
	v_add_f32_dpp v4, v4, v4 quad_perm:[2,3,0,1] row_mask:0xf bank_mask:0xf
	s_nop 1
	v_add_f32_dpp v4, v4, v4 row_half_mirror row_mask:0xf bank_mask:0xf
	s_nop 1
	v_add_f32_dpp v4, v4, v4 row_mirror row_mask:0xf bank_mask:0xf
	ds_swizzle_b32 v5, v4 offset:swizzle(SWAP,16)
	v_fma_f32 v27, v123, v23, -v16
	v_fmac_f32_e32 v26, v27, v27
	v_fma_f32 v23, v139, v23, -v17
	v_fmac_f32_e32 v26, v23, v23
	s_nop 1
	v_add_f32_dpp v16, v26, v26 quad_perm:[1,0,3,2] row_mask:0xf bank_mask:0xf
	s_nop 1
	v_add_f32_dpp v16, v16, v16 quad_perm:[2,3,0,1] row_mask:0xf bank_mask:0xf
	s_nop 1
	v_add_f32_dpp v16, v16, v16 row_half_mirror row_mask:0xf bank_mask:0xf
	s_nop 1
	v_add_f32_dpp v16, v16, v16 row_mirror row_mask:0xf bank_mask:0xf
	ds_swizzle_b32 v17, v16 offset:swizzle(SWAP,16)
	s_waitcnt lgkmcnt(0)
	v_add_f32_e32 v4, v4, v5
	v_fmamk_f32 v4, v4, 0x3c000000, v254
	s_nop 0
	s_nop 0
	s_nop 0
	s_nop 1
	s_nop 1
	s_nop 0
	v_rsq_f32_e32 v14, v4
	s_nop 0
	v_mul_f32_e32 v5, v12, v14
	v_mul_f32_e32 v12, v13, v14
	v_mul_f32_e32 v5, v7, v5
	v_mul_f32_e32 v12, v9, v12
	v_add_u32_e32 v18, 0xa000, v2
	v_cvt_pk_bf16_f32 v12, v5, v12
	v_mov_b32_e32 v19, v3
	v_lshl_add_u64 v[18:19], v[18:19], 1, s[6:7]
	global_store_short v[18:19], v12, off
	global_store_short_d16_hi v[18:19], v12, off offset:64
	v_mul_f32_e32 v4, v15, v14
	v_mul_f32_e32 v5, v11, v14
	v_mul_f32_e32 v4, v6, v4
	v_mul_f32_e32 v5, v8, v5
	v_cvt_pk_bf16_f32 v11, v4, v5
	global_store_short v[18:19], v11, off offset:128
	global_store_short_d16_hi v[18:19], v11, off offset:192
	v_add_f32_e32 v16, v16, v17
	v_fmamk_f32 v16, v16, 0x3c000000, v254
	s_nop 0
	s_nop 0
	s_nop 0
	s_nop 1
	s_nop 1
	s_nop 0
	v_rsq_f32_e32 v26, v16
	s_nop 0
	v_mul_f32_e32 v17, v24, v26
	v_mul_f32_e32 v24, v25, v26
	v_mul_f32_e32 v17, v7, v17
	v_mul_f32_e32 v24, v9, v24
	v_add_u32_e32 v20, 0xb000, v2
	v_cvt_pk_bf16_f32 v24, v17, v24
	v_mov_b32_e32 v21, v3
	v_lshl_add_u64 v[20:21], v[20:21], 1, s[6:7]
	global_store_short v[20:21], v24, off
	global_store_short_d16_hi v[20:21], v24, off offset:64
	v_mul_f32_e32 v16, v27, v26
	v_mul_f32_e32 v17, v23, v26
	v_mul_f32_e32 v16, v6, v16
	v_mul_f32_e32 v17, v8, v17
	v_cvt_pk_bf16_f32 v23, v16, v17
	global_store_short v[20:21], v23, off offset:128
	global_store_short_d16_hi v[20:21], v23, off offset:192
	ds_read_b32 v11, v10 offset:64
	ds_read2st64_b32 v[4:5], v1 offset0:8 offset1:24
	ds_read_b32 v23, v10 offset:68
	ds_read2st64_b32 v[16:17], v1 offset0:9 offset1:25
	s_waitcnt lgkmcnt(0)
	v_fma_f32 v12, v92, v11, -v4
	v_fma_f32 v13, v108, v11, -v5
	ds_read2st64_b32 v[4:5], v1 offset0:40 offset1:56
	v_mul_f32_e32 v14, v13, v13
	v_fmac_f32_e32 v14, v12, v12
	v_fma_f32 v24, v93, v23, -v16
	v_fma_f32 v25, v109, v23, -v17
	ds_read2st64_b32 v[16:17], v1 offset0:41 offset1:57
	v_mul_f32_e32 v26, v25, v25
	v_fmac_f32_e32 v26, v24, v24
	s_waitcnt lgkmcnt(0)
	v_fma_f32 v15, v124, v11, -v4
	v_fmac_f32_e32 v14, v15, v15
	v_fma_f32 v11, v140, v11, -v5
	v_fmac_f32_e32 v14, v11, v11
	s_nop 1
	v_add_f32_dpp v4, v14, v14 quad_perm:[1,0,3,2] row_mask:0xf bank_mask:0xf
	s_nop 1
	v_add_f32_dpp v4, v4, v4 quad_perm:[2,3,0,1] row_mask:0xf bank_mask:0xf
	s_nop 1
	v_add_f32_dpp v4, v4, v4 row_half_mirror row_mask:0xf bank_mask:0xf
	s_nop 1
	v_add_f32_dpp v4, v4, v4 row_mirror row_mask:0xf bank_mask:0xf
	ds_swizzle_b32 v5, v4 offset:swizzle(SWAP,16)
	v_fma_f32 v27, v125, v23, -v16
	v_fmac_f32_e32 v26, v27, v27
	v_fma_f32 v23, v141, v23, -v17
	v_fmac_f32_e32 v26, v23, v23
	s_nop 1
	v_add_f32_dpp v16, v26, v26 quad_perm:[1,0,3,2] row_mask:0xf bank_mask:0xf
	s_nop 1
	v_add_f32_dpp v16, v16, v16 quad_perm:[2,3,0,1] row_mask:0xf bank_mask:0xf
	s_nop 1
	v_add_f32_dpp v16, v16, v16 row_half_mirror row_mask:0xf bank_mask:0xf
	s_nop 1
	v_add_f32_dpp v16, v16, v16 row_mirror row_mask:0xf bank_mask:0xf
	ds_swizzle_b32 v17, v16 offset:swizzle(SWAP,16)
	s_waitcnt lgkmcnt(0)
	v_add_f32_e32 v4, v4, v5
	v_fmamk_f32 v4, v4, 0x3c000000, v254
	s_nop 0
	s_nop 0
	s_nop 0
	s_nop 1
	s_nop 1
	s_nop 0
	v_rsq_f32_e32 v14, v4
	s_nop 0
	v_mul_f32_e32 v5, v12, v14
	v_mul_f32_e32 v12, v13, v14
	v_mul_f32_e32 v5, v7, v5
	v_mul_f32_e32 v12, v9, v12
	v_add_u32_e32 v18, 0x10000, v2
	v_cvt_pk_bf16_f32 v12, v5, v12
	v_mov_b32_e32 v19, v3
	v_lshl_add_u64 v[18:19], v[18:19], 1, s[6:7]
	global_store_short v[18:19], v12, off
	global_store_short_d16_hi v[18:19], v12, off offset:64
	v_mul_f32_e32 v4, v15, v14
	v_mul_f32_e32 v5, v11, v14
	v_mul_f32_e32 v4, v6, v4
	v_mul_f32_e32 v5, v8, v5
	v_cvt_pk_bf16_f32 v11, v4, v5
	global_store_short v[18:19], v11, off offset:128
	global_store_short_d16_hi v[18:19], v11, off offset:192
	v_add_f32_e32 v16, v16, v17
	v_fmamk_f32 v16, v16, 0x3c000000, v254
	s_nop 0
	s_nop 0
	s_nop 0
	s_nop 1
	s_nop 1
	s_nop 0
	v_rsq_f32_e32 v26, v16
	s_nop 0
	v_mul_f32_e32 v17, v24, v26
	v_mul_f32_e32 v24, v25, v26
	v_mul_f32_e32 v17, v7, v17
	v_mul_f32_e32 v24, v9, v24
	v_add_u32_e32 v20, 0x11000, v2
	v_cvt_pk_bf16_f32 v24, v17, v24
	v_mov_b32_e32 v21, v3
	v_lshl_add_u64 v[20:21], v[20:21], 1, s[6:7]
	global_store_short v[20:21], v24, off
	global_store_short_d16_hi v[20:21], v24, off offset:64
	v_mul_f32_e32 v16, v27, v26
	v_mul_f32_e32 v17, v23, v26
	v_mul_f32_e32 v16, v6, v16
	v_mul_f32_e32 v17, v8, v17
	v_cvt_pk_bf16_f32 v23, v16, v17
	global_store_short v[20:21], v23, off offset:128
	global_store_short_d16_hi v[20:21], v23, off offset:192
	ds_read_b32 v11, v10 offset:72
	ds_read2st64_b32 v[4:5], v1 offset0:10 offset1:26
	ds_read_b32 v23, v10 offset:76
	ds_read2st64_b32 v[16:17], v1 offset0:11 offset1:27
	s_waitcnt lgkmcnt(0)
	v_fma_f32 v12, v94, v11, -v4
	v_fma_f32 v13, v110, v11, -v5
	ds_read2st64_b32 v[4:5], v1 offset0:42 offset1:58
	v_mul_f32_e32 v14, v13, v13
	v_fmac_f32_e32 v14, v12, v12
	v_fma_f32 v24, v95, v23, -v16
	v_fma_f32 v25, v111, v23, -v17
	ds_read2st64_b32 v[16:17], v1 offset0:43 offset1:59
	v_mul_f32_e32 v26, v25, v25
	v_fmac_f32_e32 v26, v24, v24
	s_waitcnt lgkmcnt(0)
	v_fma_f32 v15, v126, v11, -v4
	v_fmac_f32_e32 v14, v15, v15
	v_fma_f32 v11, v142, v11, -v5
	v_fmac_f32_e32 v14, v11, v11
	s_nop 1
	v_add_f32_dpp v4, v14, v14 quad_perm:[1,0,3,2] row_mask:0xf bank_mask:0xf
	s_nop 1
	v_add_f32_dpp v4, v4, v4 quad_perm:[2,3,0,1] row_mask:0xf bank_mask:0xf
	s_nop 1
	v_add_f32_dpp v4, v4, v4 row_half_mirror row_mask:0xf bank_mask:0xf
	s_nop 1
	v_add_f32_dpp v4, v4, v4 row_mirror row_mask:0xf bank_mask:0xf
	ds_swizzle_b32 v5, v4 offset:swizzle(SWAP,16)
	v_fma_f32 v27, v127, v23, -v16
	v_fmac_f32_e32 v26, v27, v27
	v_fma_f32 v23, v143, v23, -v17
	v_fmac_f32_e32 v26, v23, v23
	s_nop 1
	v_add_f32_dpp v16, v26, v26 quad_perm:[1,0,3,2] row_mask:0xf bank_mask:0xf
	s_nop 1
	v_add_f32_dpp v16, v16, v16 quad_perm:[2,3,0,1] row_mask:0xf bank_mask:0xf
	s_nop 1
	v_add_f32_dpp v16, v16, v16 row_half_mirror row_mask:0xf bank_mask:0xf
	s_nop 1
	v_add_f32_dpp v16, v16, v16 row_mirror row_mask:0xf bank_mask:0xf
	ds_swizzle_b32 v17, v16 offset:swizzle(SWAP,16)
	s_waitcnt lgkmcnt(0)
	v_add_f32_e32 v4, v4, v5
	v_fmamk_f32 v4, v4, 0x3c000000, v254
	s_nop 0
	s_nop 0
	s_nop 0
	s_nop 1
	s_nop 1
	s_nop 0
	v_rsq_f32_e32 v14, v4
	s_nop 0
	v_mul_f32_e32 v5, v12, v14
	v_mul_f32_e32 v12, v13, v14
	v_mul_f32_e32 v5, v7, v5
	v_mul_f32_e32 v12, v9, v12
	v_add_u32_e32 v18, 0x12000, v2
	v_cvt_pk_bf16_f32 v12, v5, v12
	v_mov_b32_e32 v19, v3
	v_lshl_add_u64 v[18:19], v[18:19], 1, s[6:7]
	global_store_short v[18:19], v12, off
	global_store_short_d16_hi v[18:19], v12, off offset:64
	v_mul_f32_e32 v4, v15, v14
	v_mul_f32_e32 v5, v11, v14
	v_mul_f32_e32 v4, v6, v4
	v_mul_f32_e32 v5, v8, v5
	v_cvt_pk_bf16_f32 v11, v4, v5
	global_store_short v[18:19], v11, off offset:128
	global_store_short_d16_hi v[18:19], v11, off offset:192
	v_add_f32_e32 v16, v16, v17
	v_fmamk_f32 v16, v16, 0x3c000000, v254
	s_nop 0
	s_nop 0
	s_nop 0
	s_nop 1
	s_nop 1
	s_nop 0
	v_rsq_f32_e32 v26, v16
	s_nop 0
	v_mul_f32_e32 v17, v24, v26
	v_mul_f32_e32 v24, v25, v26
	v_mul_f32_e32 v17, v7, v17
	v_mul_f32_e32 v24, v9, v24
	v_add_u32_e32 v20, 0x13000, v2
	v_cvt_pk_bf16_f32 v24, v17, v24
	v_mov_b32_e32 v21, v3
	v_lshl_add_u64 v[20:21], v[20:21], 1, s[6:7]
	global_store_short v[20:21], v24, off
	global_store_short_d16_hi v[20:21], v24, off offset:64
	v_mul_f32_e32 v16, v27, v26
	v_mul_f32_e32 v17, v23, v26
	v_mul_f32_e32 v16, v6, v16
	v_mul_f32_e32 v17, v8, v17
	v_cvt_pk_bf16_f32 v23, v16, v17
	global_store_short v[20:21], v23, off offset:128
	global_store_short_d16_hi v[20:21], v23, off offset:192
	ds_read_b32 v11, v10 offset:96
	ds_read2st64_b32 v[4:5], v1 offset0:12 offset1:28
	ds_read_b32 v23, v10 offset:100
	ds_read2st64_b32 v[16:17], v1 offset0:13 offset1:29
	s_waitcnt lgkmcnt(0)
	v_fma_f32 v12, v96, v11, -v4
	v_fma_f32 v13, v112, v11, -v5
	ds_read2st64_b32 v[4:5], v1 offset0:44 offset1:60
	v_mul_f32_e32 v14, v13, v13
	v_fmac_f32_e32 v14, v12, v12
	v_fma_f32 v24, v97, v23, -v16
	v_fma_f32 v25, v113, v23, -v17
	ds_read2st64_b32 v[16:17], v1 offset0:45 offset1:61
	v_mul_f32_e32 v26, v25, v25
	v_fmac_f32_e32 v26, v24, v24
	s_waitcnt lgkmcnt(0)
	v_fma_f32 v15, v128, v11, -v4
	v_fmac_f32_e32 v14, v15, v15
	v_fma_f32 v11, v144, v11, -v5
	v_fmac_f32_e32 v14, v11, v11
	s_nop 1
	v_add_f32_dpp v4, v14, v14 quad_perm:[1,0,3,2] row_mask:0xf bank_mask:0xf
	s_nop 1
	v_add_f32_dpp v4, v4, v4 quad_perm:[2,3,0,1] row_mask:0xf bank_mask:0xf
	s_nop 1
	v_add_f32_dpp v4, v4, v4 row_half_mirror row_mask:0xf bank_mask:0xf
	s_nop 1
	v_add_f32_dpp v4, v4, v4 row_mirror row_mask:0xf bank_mask:0xf
	ds_swizzle_b32 v5, v4 offset:swizzle(SWAP,16)
	v_fma_f32 v27, v129, v23, -v16
	v_fmac_f32_e32 v26, v27, v27
	v_fma_f32 v23, v145, v23, -v17
	v_fmac_f32_e32 v26, v23, v23
	s_nop 1
	v_add_f32_dpp v16, v26, v26 quad_perm:[1,0,3,2] row_mask:0xf bank_mask:0xf
	s_nop 1
	v_add_f32_dpp v16, v16, v16 quad_perm:[2,3,0,1] row_mask:0xf bank_mask:0xf
	s_nop 1
	v_add_f32_dpp v16, v16, v16 row_half_mirror row_mask:0xf bank_mask:0xf
	s_nop 1
	v_add_f32_dpp v16, v16, v16 row_mirror row_mask:0xf bank_mask:0xf
	ds_swizzle_b32 v17, v16 offset:swizzle(SWAP,16)
	s_waitcnt lgkmcnt(0)
	v_add_f32_e32 v4, v4, v5
	v_fmamk_f32 v4, v4, 0x3c000000, v254
	s_nop 0
	s_nop 0
	s_nop 0
	s_nop 1
	s_nop 1
	s_nop 0
	v_rsq_f32_e32 v14, v4
	s_nop 0
	v_mul_f32_e32 v5, v12, v14
	v_mul_f32_e32 v12, v13, v14
	v_mul_f32_e32 v5, v7, v5
	v_mul_f32_e32 v12, v9, v12
	v_add_u32_e32 v18, 0x18000, v2
	v_cvt_pk_bf16_f32 v12, v5, v12
	v_mov_b32_e32 v19, v3
	v_lshl_add_u64 v[18:19], v[18:19], 1, s[6:7]
	global_store_short v[18:19], v12, off
	global_store_short_d16_hi v[18:19], v12, off offset:64
	v_mul_f32_e32 v4, v15, v14
	v_mul_f32_e32 v5, v11, v14
	v_mul_f32_e32 v4, v6, v4
	v_mul_f32_e32 v5, v8, v5
	v_cvt_pk_bf16_f32 v11, v4, v5
	global_store_short v[18:19], v11, off offset:128
	global_store_short_d16_hi v[18:19], v11, off offset:192
	v_add_f32_e32 v16, v16, v17
	v_fmamk_f32 v16, v16, 0x3c000000, v254
	s_nop 0
	s_nop 0
	s_nop 0
	s_nop 1
	s_nop 1
	s_nop 0
	v_rsq_f32_e32 v26, v16
	s_nop 0
	v_mul_f32_e32 v17, v24, v26
	v_mul_f32_e32 v24, v25, v26
	v_mul_f32_e32 v17, v7, v17
	v_mul_f32_e32 v24, v9, v24
	v_add_u32_e32 v20, 0x19000, v2
	v_cvt_pk_bf16_f32 v24, v17, v24
	v_mov_b32_e32 v21, v3
	v_lshl_add_u64 v[20:21], v[20:21], 1, s[6:7]
	global_store_short v[20:21], v24, off
	global_store_short_d16_hi v[20:21], v24, off offset:64
	v_mul_f32_e32 v16, v27, v26
	v_mul_f32_e32 v17, v23, v26
	v_mul_f32_e32 v16, v6, v16
	v_mul_f32_e32 v17, v8, v17
	v_cvt_pk_bf16_f32 v23, v16, v17
	global_store_short v[20:21], v23, off offset:128
	global_store_short_d16_hi v[20:21], v23, off offset:192
	ds_read_b32 v11, v10 offset:104
	ds_read2st64_b32 v[4:5], v1 offset0:14 offset1:30
	s_waitcnt lgkmcnt(0)
	v_fma_f32 v12, v98, v11, -v4
	v_fma_f32 v13, v114, v11, -v5
	ds_read2st64_b32 v[4:5], v1 offset0:46 offset1:62
	v_mul_f32_e32 v14, v13, v13
	v_fmac_f32_e32 v14, v12, v12
	s_waitcnt lgkmcnt(0)
	v_fma_f32 v15, v130, v11, -v4
	v_fmac_f32_e32 v14, v15, v15
	v_fma_f32 v11, v146, v11, -v5
	v_fmac_f32_e32 v14, v11, v11
	s_nop 1
	v_add_f32_dpp v4, v14, v14 quad_perm:[1,0,3,2] row_mask:0xf bank_mask:0xf
	s_nop 1
	v_add_f32_dpp v4, v4, v4 quad_perm:[2,3,0,1] row_mask:0xf bank_mask:0xf
	s_nop 1
	v_add_f32_dpp v4, v4, v4 row_half_mirror row_mask:0xf bank_mask:0xf
	s_nop 1
	v_add_f32_dpp v4, v4, v4 row_mirror row_mask:0xf bank_mask:0xf
	ds_swizzle_b32 v5, v4 offset:swizzle(SWAP,16)
	s_waitcnt lgkmcnt(0)
	v_add_f32_e32 v4, v4, v5
	v_fmamk_f32 v4, v4, 0x3c000000, v254
	s_nop 0
	s_nop 0
	s_nop 0
	s_nop 1
	s_nop 1
	s_nop 0
	v_rsq_f32_e32 v14, v4
	s_nop 0
	v_mul_f32_e32 v5, v12, v14
	v_mul_f32_e32 v12, v13, v14
	v_mul_f32_e32 v5, v7, v5
	v_mul_f32_e32 v12, v9, v12
	v_add_u32_e32 v18, 0x1a000, v2
	v_cvt_pk_bf16_f32 v12, v5, v12
	v_mov_b32_e32 v19, v3
	v_lshl_add_u64 v[18:19], v[18:19], 1, s[6:7]
	global_store_short v[18:19], v12, off
	global_store_short_d16_hi v[18:19], v12, off offset:64
	v_mul_f32_e32 v4, v15, v14
	v_mul_f32_e32 v5, v11, v14
	v_mul_f32_e32 v4, v6, v4
	v_mul_f32_e32 v5, v8, v5
	v_cvt_pk_bf16_f32 v11, v4, v5
	global_store_short v[18:19], v11, off offset:128
	global_store_short_d16_hi v[18:19], v11, off offset:192
	ds_read_b32 v10, v10 offset:108
	ds_read2st64_b32 v[4:5], v1 offset0:15 offset1:31
	s_waitcnt lgkmcnt(0)
	v_fma_f32 v11, v99, v10, -v4
	v_fma_f32 v12, v115, v10, -v5
	ds_read2st64_b32 v[4:5], v1 offset0:47 offset1:63
	v_mul_f32_e32 v13, v12, v12
	v_fmac_f32_e32 v13, v11, v11
	s_waitcnt lgkmcnt(0)
	v_fma_f32 v1, v131, v10, -v4
	v_fmac_f32_e32 v13, v1, v1
	v_fma_f32 v10, v147, v10, -v5
	v_fmac_f32_e32 v13, v10, v10
	s_nop 1
	v_add_f32_dpp v4, v13, v13 quad_perm:[1,0,3,2] row_mask:0xf bank_mask:0xf
	s_nop 1
	v_add_f32_dpp v4, v4, v4 quad_perm:[2,3,0,1] row_mask:0xf bank_mask:0xf
	s_nop 1
	v_add_f32_dpp v4, v4, v4 row_half_mirror row_mask:0xf bank_mask:0xf
	s_nop 1
	v_add_f32_dpp v4, v4, v4 row_mirror row_mask:0xf bank_mask:0xf
	ds_swizzle_b32 v5, v4 offset:swizzle(SWAP,16)
	s_waitcnt lgkmcnt(0)
	v_add_f32_e32 v4, v4, v5
	v_fmamk_f32 v4, v4, 0x3c000000, v254
	s_nop 0
	s_nop 0
	s_nop 0
	s_nop 1
	s_nop 1
	s_nop 0
	v_rsq_f32_e32 v13, v4
	s_nop 0
	v_mul_f32_e32 v5, v11, v13
	v_mul_f32_e32 v5, v7, v5
	v_mul_f32_e32 v7, v12, v13
	v_mul_f32_e32 v7, v9, v7
	v_add_u32_e32 v4, 0x1b000, v2
	v_cvt_pk_bf16_f32 v7, v5, v7
	v_mov_b32_e32 v5, v3
	v_lshl_add_u64 v[4:5], v[4:5], 1, s[6:7]
	global_store_short v[4:5], v7, off
	v_add_u32_e32 v4, 0x1b020, v2
	v_mov_b32_e32 v5, v3
	v_lshl_add_u64 v[4:5], v[4:5], 1, s[6:7]
	global_store_short_d16_hi v[4:5], v7, off
	v_mul_f32_e32 v1, v1, v13
	v_mul_f32_e32 v4, v10, v13
	v_mul_f32_e32 v1, v6, v1
	v_mul_f32_e32 v4, v8, v4
	v_cvt_pk_bf16_f32 v1, v1, v4
	v_add_u32_e32 v4, 0x1b040, v2
	v_mov_b32_e32 v5, v3
	v_lshl_add_u64 v[4:5], v[4:5], 1, s[6:7]
	v_add_u32_e32 v2, 0x1b060, v2
	global_store_short v[4:5], v1, off
	v_lshl_add_u64 v[4:5], v[2:3], 1, s[6:7]
	global_store_short_d16_hi v[4:5], v1, off

.LBB0_1239:
	s_or_b64 exec, exec, s[4:5]
	s_waitcnt lgkmcnt(0)
	v_lshlrev_b32_e32 v2, 2, v158
	global_load_dword v249, v2, s[0:1]
	global_load_dword v250, v2, s[0:1] offset:128
	global_load_dword v251, v2, s[0:1] offset:256
	global_load_dword v253, v2, s[0:1] offset:384
	v_add_u32_e32 v10, s43, v148
	s_lshl_b64 s[4:5], s[24:25], 13
	s_add_u32 s4, s86, s4
	s_addc_u32 s5, s87, s5
	s_lshl_b32 s6, s8, 1
	s_add_u32 s6, s4, s6
	s_addc_u32 s7, s5, 0
	s_waitcnt vmcnt(0)
	v_mul_f32_e32 v7, v164, v249
	v_mul_f32_e32 v9, v164, v250
	v_mul_f32_e32 v6, v164, v251
	v_mul_f32_e32 v8, v164, v253
	v_lshl_or_b32 v2, v159, 14, v158
	ds_read_b32 v11, v10
	ds_read2st64_b32 v[4:5], v1 offset1:16
	ds_read_b32 v23, v10 offset:4
	ds_read2st64_b32 v[16:17], v1 offset0:1 offset1:17
	s_waitcnt lgkmcnt(0)
	v_fma_f32 v12, v68, v11, -v4
	v_fma_f32 v13, v84, v11, -v5
	ds_read2st64_b32 v[4:5], v1 offset0:32 offset1:48
	v_mul_f32_e32 v14, v13, v13
	v_fmac_f32_e32 v14, v12, v12
	v_fma_f32 v24, v69, v23, -v16
	v_fma_f32 v25, v85, v23, -v17
	ds_read2st64_b32 v[16:17], v1 offset0:33 offset1:49
	v_mul_f32_e32 v26, v25, v25
	v_fmac_f32_e32 v26, v24, v24
	s_waitcnt lgkmcnt(0)
	v_fma_f32 v15, v100, v11, -v4
	v_fmac_f32_e32 v14, v15, v15
	v_fma_f32 v11, v116, v11, -v5
	v_fmac_f32_e32 v14, v11, v11
	s_nop 1
	v_add_f32_dpp v4, v14, v14 quad_perm:[1,0,3,2] row_mask:0xf bank_mask:0xf
	s_nop 1
	v_add_f32_dpp v4, v4, v4 quad_perm:[2,3,0,1] row_mask:0xf bank_mask:0xf
	s_nop 1
	v_add_f32_dpp v4, v4, v4 row_half_mirror row_mask:0xf bank_mask:0xf
	s_nop 1
	v_add_f32_dpp v4, v4, v4 row_mirror row_mask:0xf bank_mask:0xf
	ds_swizzle_b32 v5, v4 offset:swizzle(SWAP,16)
	v_fma_f32 v27, v101, v23, -v16
	v_fmac_f32_e32 v26, v27, v27
	v_fma_f32 v23, v117, v23, -v17
	v_fmac_f32_e32 v26, v23, v23
	s_nop 1
	v_add_f32_dpp v16, v26, v26 quad_perm:[1,0,3,2] row_mask:0xf bank_mask:0xf
	s_nop 1
	v_add_f32_dpp v16, v16, v16 quad_perm:[2,3,0,1] row_mask:0xf bank_mask:0xf
	s_nop 1
	v_add_f32_dpp v16, v16, v16 row_half_mirror row_mask:0xf bank_mask:0xf
	s_nop 1
	v_add_f32_dpp v16, v16, v16 row_mirror row_mask:0xf bank_mask:0xf
	ds_swizzle_b32 v17, v16 offset:swizzle(SWAP,16)
	s_waitcnt lgkmcnt(0)
	v_add_f32_e32 v4, v4, v5
	v_fmamk_f32 v4, v4, 0x3c000000, v254
	s_nop 0
	s_nop 0
	s_nop 0
	s_nop 1
	s_nop 1
	s_nop 0
	v_rsq_f32_e32 v14, v4
	s_nop 0
	v_mul_f32_e32 v4, v12, v14
	v_mul_f32_e32 v5, v13, v14
	v_mul_f32_e32 v4, v7, v4
	v_mul_f32_e32 v5, v9, v5
	v_cvt_pk_bf16_f32 v12, v4, v5
	v_lshl_add_u64 v[4:5], v[2:3], 1, s[6:7]
	global_store_short v[4:5], v12, off
	v_add_u32_e32 v4, 32, v2
	v_mov_b32_e32 v5, v3
	v_lshl_add_u64 v[4:5], v[4:5], 1, s[6:7]
	global_store_short_d16_hi v[4:5], v12, off
	v_mul_f32_e32 v4, v15, v14
	v_mul_f32_e32 v5, v11, v14
	v_mul_f32_e32 v4, v6, v4
	v_mul_f32_e32 v5, v8, v5
	v_cvt_pk_bf16_f32 v11, v4, v5
	v_add_u32_e32 v4, 64, v2
	v_mov_b32_e32 v5, v3
	v_lshl_add_u64 v[4:5], v[4:5], 1, s[6:7]
	global_store_short v[4:5], v11, off
	v_add_u32_e32 v4, 0x60, v2
	v_mov_b32_e32 v5, v3
	v_lshl_add_u64 v[4:5], v[4:5], 1, s[6:7]
	global_store_short_d16_hi v[4:5], v11, off
	v_add_f32_e32 v16, v16, v17
	v_fmamk_f32 v16, v16, 0x3c000000, v254
	s_nop 0
	s_nop 0
	s_nop 0
	s_nop 1
	s_nop 1
	s_nop 0
	v_rsq_f32_e32 v26, v16
	s_nop 0
	v_mul_f32_e32 v17, v24, v26
	v_mul_f32_e32 v24, v25, v26
	v_mul_f32_e32 v17, v7, v17
	v_mul_f32_e32 v24, v9, v24
	v_add_u32_e32 v20, 0x1000, v2
	v_cvt_pk_bf16_f32 v24, v17, v24
	v_mov_b32_e32 v21, v3
	v_lshl_add_u64 v[20:21], v[20:21], 1, s[6:7]
	global_store_short v[20:21], v24, off
	global_store_short_d16_hi v[20:21], v24, off offset:64
	v_mul_f32_e32 v16, v27, v26
	v_mul_f32_e32 v17, v23, v26
	v_mul_f32_e32 v16, v6, v16
	v_mul_f32_e32 v17, v8, v17
	v_cvt_pk_bf16_f32 v23, v16, v17
	global_store_short v[20:21], v23, off offset:128
	global_store_short_d16_hi v[20:21], v23, off offset:192
	ds_read_b32 v11, v10 offset:8
	ds_read2st64_b32 v[4:5], v1 offset0:2 offset1:18
	ds_read_b32 v23, v10 offset:12
	ds_read2st64_b32 v[16:17], v1 offset0:3 offset1:19
	s_waitcnt lgkmcnt(0)
	v_fma_f32 v12, v70, v11, -v4
	v_fma_f32 v13, v86, v11, -v5
	ds_read2st64_b32 v[4:5], v1 offset0:34 offset1:50
	v_mul_f32_e32 v14, v13, v13
	v_fmac_f32_e32 v14, v12, v12
	v_fma_f32 v24, v71, v23, -v16
	v_fma_f32 v25, v87, v23, -v17
	ds_read2st64_b32 v[16:17], v1 offset0:35 offset1:51
	v_mul_f32_e32 v26, v25, v25
	v_fmac_f32_e32 v26, v24, v24
	s_waitcnt lgkmcnt(0)
	v_fma_f32 v15, v102, v11, -v4
	v_fmac_f32_e32 v14, v15, v15
	v_fma_f32 v11, v118, v11, -v5
	v_fmac_f32_e32 v14, v11, v11
	s_nop 1
	v_add_f32_dpp v4, v14, v14 quad_perm:[1,0,3,2] row_mask:0xf bank_mask:0xf
	s_nop 1
	v_add_f32_dpp v4, v4, v4 quad_perm:[2,3,0,1] row_mask:0xf bank_mask:0xf
	s_nop 1
	v_add_f32_dpp v4, v4, v4 row_half_mirror row_mask:0xf bank_mask:0xf
	s_nop 1
	v_add_f32_dpp v4, v4, v4 row_mirror row_mask:0xf bank_mask:0xf
	ds_swizzle_b32 v5, v4 offset:swizzle(SWAP,16)
	v_fma_f32 v27, v103, v23, -v16
	v_fmac_f32_e32 v26, v27, v27
	v_fma_f32 v23, v119, v23, -v17
	v_fmac_f32_e32 v26, v23, v23
	s_nop 1
	v_add_f32_dpp v16, v26, v26 quad_perm:[1,0,3,2] row_mask:0xf bank_mask:0xf
	s_nop 1
	v_add_f32_dpp v16, v16, v16 quad_perm:[2,3,0,1] row_mask:0xf bank_mask:0xf
	s_nop 1
	v_add_f32_dpp v16, v16, v16 row_half_mirror row_mask:0xf bank_mask:0xf
	s_nop 1
	v_add_f32_dpp v16, v16, v16 row_mirror row_mask:0xf bank_mask:0xf
	ds_swizzle_b32 v17, v16 offset:swizzle(SWAP,16)
	s_waitcnt lgkmcnt(0)
	v_add_f32_e32 v4, v4, v5
	v_fmamk_f32 v4, v4, 0x3c000000, v254
	s_nop 0
	s_nop 0
	s_nop 0
	s_nop 1
	s_nop 1
	s_nop 0
	v_rsq_f32_e32 v14, v4
	s_nop 0
	v_mul_f32_e32 v5, v12, v14
	v_mul_f32_e32 v12, v13, v14
	v_mul_f32_e32 v5, v7, v5
	v_mul_f32_e32 v12, v9, v12
	v_add_u32_e32 v18, 0x2000, v2
	v_cvt_pk_bf16_f32 v12, v5, v12
	v_mov_b32_e32 v19, v3
	v_lshl_add_u64 v[18:19], v[18:19], 1, s[6:7]
	global_store_short v[18:19], v12, off
	global_store_short_d16_hi v[18:19], v12, off offset:64
	v_mul_f32_e32 v4, v15, v14
	v_mul_f32_e32 v5, v11, v14
	v_mul_f32_e32 v4, v6, v4
	v_mul_f32_e32 v5, v8, v5
	v_cvt_pk_bf16_f32 v11, v4, v5
	global_store_short v[18:19], v11, off offset:128
	global_store_short_d16_hi v[18:19], v11, off offset:192
	v_add_f32_e32 v16, v16, v17
	v_fmamk_f32 v16, v16, 0x3c000000, v254
	s_nop 0
	s_nop 0
	s_nop 0
	s_nop 1
	s_nop 1
	s_nop 0
	v_rsq_f32_e32 v26, v16
	s_nop 0
	v_mul_f32_e32 v17, v24, v26
	v_mul_f32_e32 v24, v25, v26
	v_mul_f32_e32 v17, v7, v17
	v_mul_f32_e32 v24, v9, v24
	v_add_u32_e32 v20, 0x3000, v2
	v_cvt_pk_bf16_f32 v24, v17, v24
	v_mov_b32_e32 v21, v3
	v_lshl_add_u64 v[20:21], v[20:21], 1, s[6:7]
	global_store_short v[20:21], v24, off
	global_store_short_d16_hi v[20:21], v24, off offset:64
	v_mul_f32_e32 v16, v27, v26
	v_mul_f32_e32 v17, v23, v26
	v_mul_f32_e32 v16, v6, v16
	v_mul_f32_e32 v17, v8, v17
	v_cvt_pk_bf16_f32 v23, v16, v17
	global_store_short v[20:21], v23, off offset:128
	global_store_short_d16_hi v[20:21], v23, off offset:192
	ds_read_b32 v11, v10 offset:32
	ds_read2st64_b32 v[4:5], v1 offset0:4 offset1:20
	ds_read_b32 v23, v10 offset:36
	ds_read2st64_b32 v[16:17], v1 offset0:5 offset1:21
	s_waitcnt lgkmcnt(0)
	v_fma_f32 v12, v72, v11, -v4
	v_fma_f32 v13, v88, v11, -v5
	ds_read2st64_b32 v[4:5], v1 offset0:36 offset1:52
	v_mul_f32_e32 v14, v13, v13
	v_fmac_f32_e32 v14, v12, v12
	v_fma_f32 v24, v73, v23, -v16
	v_fma_f32 v25, v89, v23, -v17
	ds_read2st64_b32 v[16:17], v1 offset0:37 offset1:53
	v_mul_f32_e32 v26, v25, v25
	v_fmac_f32_e32 v26, v24, v24
	s_waitcnt lgkmcnt(0)
	v_fma_f32 v15, v104, v11, -v4
	v_fmac_f32_e32 v14, v15, v15
	v_fma_f32 v11, v120, v11, -v5
	v_fmac_f32_e32 v14, v11, v11
	s_nop 1
	v_add_f32_dpp v4, v14, v14 quad_perm:[1,0,3,2] row_mask:0xf bank_mask:0xf
	s_nop 1
	v_add_f32_dpp v4, v4, v4 quad_perm:[2,3,0,1] row_mask:0xf bank_mask:0xf
	s_nop 1
	v_add_f32_dpp v4, v4, v4 row_half_mirror row_mask:0xf bank_mask:0xf
	s_nop 1
	v_add_f32_dpp v4, v4, v4 row_mirror row_mask:0xf bank_mask:0xf
	ds_swizzle_b32 v5, v4 offset:swizzle(SWAP,16)
	v_fma_f32 v27, v105, v23, -v16
	v_fmac_f32_e32 v26, v27, v27
	v_fma_f32 v23, v121, v23, -v17
	v_fmac_f32_e32 v26, v23, v23
	s_nop 1
	v_add_f32_dpp v16, v26, v26 quad_perm:[1,0,3,2] row_mask:0xf bank_mask:0xf
	s_nop 1
	v_add_f32_dpp v16, v16, v16 quad_perm:[2,3,0,1] row_mask:0xf bank_mask:0xf
	s_nop 1
	v_add_f32_dpp v16, v16, v16 row_half_mirror row_mask:0xf bank_mask:0xf
	s_nop 1
	v_add_f32_dpp v16, v16, v16 row_mirror row_mask:0xf bank_mask:0xf
	ds_swizzle_b32 v17, v16 offset:swizzle(SWAP,16)
	s_waitcnt lgkmcnt(0)
	v_add_f32_e32 v4, v4, v5
	v_fmamk_f32 v4, v4, 0x3c000000, v254
	s_nop 0
	s_nop 0
	s_nop 0
	s_nop 1
	s_nop 1
	s_nop 0
	v_rsq_f32_e32 v14, v4
	s_nop 0
	v_mul_f32_e32 v5, v12, v14
	v_mul_f32_e32 v12, v13, v14
	v_mul_f32_e32 v5, v7, v5
	v_mul_f32_e32 v12, v9, v12
	v_add_u32_e32 v18, 0x8000, v2
	v_cvt_pk_bf16_f32 v12, v5, v12
	v_mov_b32_e32 v19, v3
	v_lshl_add_u64 v[18:19], v[18:19], 1, s[6:7]
	global_store_short v[18:19], v12, off
	global_store_short_d16_hi v[18:19], v12, off offset:64
	v_mul_f32_e32 v4, v15, v14
	v_mul_f32_e32 v5, v11, v14
	v_mul_f32_e32 v4, v6, v4
	v_mul_f32_e32 v5, v8, v5
	v_cvt_pk_bf16_f32 v11, v4, v5
	global_store_short v[18:19], v11, off offset:128
	global_store_short_d16_hi v[18:19], v11, off offset:192
	v_add_f32_e32 v16, v16, v17
	v_fmamk_f32 v16, v16, 0x3c000000, v254
	s_nop 0
	s_nop 0
	s_nop 0
	s_nop 1
	s_nop 1
	s_nop 0
	v_rsq_f32_e32 v26, v16
	s_nop 0
	v_mul_f32_e32 v17, v24, v26
	v_mul_f32_e32 v24, v25, v26
	v_mul_f32_e32 v17, v7, v17
	v_mul_f32_e32 v24, v9, v24
	v_add_u32_e32 v20, 0x9000, v2
	v_cvt_pk_bf16_f32 v24, v17, v24
	v_mov_b32_e32 v21, v3
	v_lshl_add_u64 v[20:21], v[20:21], 1, s[6:7]
	global_store_short v[20:21], v24, off
	global_store_short_d16_hi v[20:21], v24, off offset:64
	v_mul_f32_e32 v16, v27, v26
	v_mul_f32_e32 v17, v23, v26
	v_mul_f32_e32 v16, v6, v16
	v_mul_f32_e32 v17, v8, v17
	v_cvt_pk_bf16_f32 v23, v16, v17
	global_store_short v[20:21], v23, off offset:128
	global_store_short_d16_hi v[20:21], v23, off offset:192
	ds_read_b32 v11, v10 offset:40
	ds_read2st64_b32 v[4:5], v1 offset0:6 offset1:22
	ds_read_b32 v23, v10 offset:44
	ds_read2st64_b32 v[16:17], v1 offset0:7 offset1:23
	s_waitcnt lgkmcnt(0)
	v_fma_f32 v12, v74, v11, -v4
	v_fma_f32 v13, v90, v11, -v5
	ds_read2st64_b32 v[4:5], v1 offset0:38 offset1:54
	v_mul_f32_e32 v14, v13, v13
	v_fmac_f32_e32 v14, v12, v12
	v_fma_f32 v24, v75, v23, -v16
	v_fma_f32 v25, v91, v23, -v17
	ds_read2st64_b32 v[16:17], v1 offset0:39 offset1:55
	v_mul_f32_e32 v26, v25, v25
	v_fmac_f32_e32 v26, v24, v24
	s_waitcnt lgkmcnt(0)
	v_fma_f32 v15, v106, v11, -v4
	v_fmac_f32_e32 v14, v15, v15
	v_fma_f32 v11, v122, v11, -v5
	v_fmac_f32_e32 v14, v11, v11
	s_nop 1
	v_add_f32_dpp v4, v14, v14 quad_perm:[1,0,3,2] row_mask:0xf bank_mask:0xf
	s_nop 1
	v_add_f32_dpp v4, v4, v4 quad_perm:[2,3,0,1] row_mask:0xf bank_mask:0xf
	s_nop 1
	v_add_f32_dpp v4, v4, v4 row_half_mirror row_mask:0xf bank_mask:0xf
	s_nop 1
	v_add_f32_dpp v4, v4, v4 row_mirror row_mask:0xf bank_mask:0xf
	ds_swizzle_b32 v5, v4 offset:swizzle(SWAP,16)
	v_fma_f32 v27, v107, v23, -v16
	v_fmac_f32_e32 v26, v27, v27
	v_fma_f32 v23, v123, v23, -v17
	v_fmac_f32_e32 v26, v23, v23
	s_nop 1
	v_add_f32_dpp v16, v26, v26 quad_perm:[1,0,3,2] row_mask:0xf bank_mask:0xf
	s_nop 1
	v_add_f32_dpp v16, v16, v16 quad_perm:[2,3,0,1] row_mask:0xf bank_mask:0xf
	s_nop 1
	v_add_f32_dpp v16, v16, v16 row_half_mirror row_mask:0xf bank_mask:0xf
	s_nop 1
	v_add_f32_dpp v16, v16, v16 row_mirror row_mask:0xf bank_mask:0xf
	ds_swizzle_b32 v17, v16 offset:swizzle(SWAP,16)
	s_waitcnt lgkmcnt(0)
	v_add_f32_e32 v4, v4, v5
	v_fmamk_f32 v4, v4, 0x3c000000, v254
	s_nop 0
	s_nop 0
	s_nop 0
	s_nop 1
	s_nop 1
	s_nop 0
	v_rsq_f32_e32 v14, v4
	s_nop 0
	v_mul_f32_e32 v5, v12, v14
	v_mul_f32_e32 v12, v13, v14
	v_mul_f32_e32 v5, v7, v5
	v_mul_f32_e32 v12, v9, v12
	v_add_u32_e32 v18, 0xa000, v2
	v_cvt_pk_bf16_f32 v12, v5, v12
	v_mov_b32_e32 v19, v3
	v_lshl_add_u64 v[18:19], v[18:19], 1, s[6:7]
	global_store_short v[18:19], v12, off
	global_store_short_d16_hi v[18:19], v12, off offset:64
	v_mul_f32_e32 v4, v15, v14
	v_mul_f32_e32 v5, v11, v14
	v_mul_f32_e32 v4, v6, v4
	v_mul_f32_e32 v5, v8, v5
	v_cvt_pk_bf16_f32 v11, v4, v5
	global_store_short v[18:19], v11, off offset:128
	global_store_short_d16_hi v[18:19], v11, off offset:192
	v_add_f32_e32 v16, v16, v17
	v_fmamk_f32 v16, v16, 0x3c000000, v254
	s_nop 0
	s_nop 0
	s_nop 0
	s_nop 1
	s_nop 1
	s_nop 0
	v_rsq_f32_e32 v26, v16
	s_nop 0
	v_mul_f32_e32 v17, v24, v26
	v_mul_f32_e32 v24, v25, v26
	v_mul_f32_e32 v17, v7, v17
	v_mul_f32_e32 v24, v9, v24
	v_add_u32_e32 v20, 0xb000, v2
	v_cvt_pk_bf16_f32 v24, v17, v24
	v_mov_b32_e32 v21, v3
	v_lshl_add_u64 v[20:21], v[20:21], 1, s[6:7]
	global_store_short v[20:21], v24, off
	global_store_short_d16_hi v[20:21], v24, off offset:64
	v_mul_f32_e32 v16, v27, v26
	v_mul_f32_e32 v17, v23, v26
	v_mul_f32_e32 v16, v6, v16
	v_mul_f32_e32 v17, v8, v17
	v_cvt_pk_bf16_f32 v23, v16, v17
	global_store_short v[20:21], v23, off offset:128
	global_store_short_d16_hi v[20:21], v23, off offset:192
	ds_read_b32 v11, v10 offset:64
	ds_read2st64_b32 v[4:5], v1 offset0:8 offset1:24
	ds_read_b32 v23, v10 offset:68
	ds_read2st64_b32 v[16:17], v1 offset0:9 offset1:25
	s_waitcnt lgkmcnt(0)
	v_fma_f32 v12, v76, v11, -v4
	v_fma_f32 v13, v92, v11, -v5
	ds_read2st64_b32 v[4:5], v1 offset0:40 offset1:56
	v_mul_f32_e32 v14, v13, v13
	v_fmac_f32_e32 v14, v12, v12
	v_fma_f32 v24, v77, v23, -v16
	v_fma_f32 v25, v93, v23, -v17
	ds_read2st64_b32 v[16:17], v1 offset0:41 offset1:57
	v_mul_f32_e32 v26, v25, v25
	v_fmac_f32_e32 v26, v24, v24
	s_waitcnt lgkmcnt(0)
	v_fma_f32 v15, v108, v11, -v4
	v_fmac_f32_e32 v14, v15, v15
	v_fma_f32 v11, v124, v11, -v5
	v_fmac_f32_e32 v14, v11, v11
	s_nop 1
	v_add_f32_dpp v4, v14, v14 quad_perm:[1,0,3,2] row_mask:0xf bank_mask:0xf
	s_nop 1
	v_add_f32_dpp v4, v4, v4 quad_perm:[2,3,0,1] row_mask:0xf bank_mask:0xf
	s_nop 1
	v_add_f32_dpp v4, v4, v4 row_half_mirror row_mask:0xf bank_mask:0xf
	s_nop 1
	v_add_f32_dpp v4, v4, v4 row_mirror row_mask:0xf bank_mask:0xf
	ds_swizzle_b32 v5, v4 offset:swizzle(SWAP,16)
	v_fma_f32 v27, v109, v23, -v16
	v_fmac_f32_e32 v26, v27, v27
	v_fma_f32 v23, v125, v23, -v17
	v_fmac_f32_e32 v26, v23, v23
	s_nop 1
	v_add_f32_dpp v16, v26, v26 quad_perm:[1,0,3,2] row_mask:0xf bank_mask:0xf
	s_nop 1
	v_add_f32_dpp v16, v16, v16 quad_perm:[2,3,0,1] row_mask:0xf bank_mask:0xf
	s_nop 1
	v_add_f32_dpp v16, v16, v16 row_half_mirror row_mask:0xf bank_mask:0xf
	s_nop 1
	v_add_f32_dpp v16, v16, v16 row_mirror row_mask:0xf bank_mask:0xf
	ds_swizzle_b32 v17, v16 offset:swizzle(SWAP,16)
	s_waitcnt lgkmcnt(0)
	v_add_f32_e32 v4, v4, v5
	v_fmamk_f32 v4, v4, 0x3c000000, v254
	s_nop 0
	s_nop 0
	s_nop 0
	s_nop 1
	s_nop 1
	s_nop 0
	v_rsq_f32_e32 v14, v4
	s_nop 0
	v_mul_f32_e32 v5, v12, v14
	v_mul_f32_e32 v12, v13, v14
	v_mul_f32_e32 v5, v7, v5
	v_mul_f32_e32 v12, v9, v12
	v_add_u32_e32 v18, 0x10000, v2
	v_cvt_pk_bf16_f32 v12, v5, v12
	v_mov_b32_e32 v19, v3
	v_lshl_add_u64 v[18:19], v[18:19], 1, s[6:7]
	global_store_short v[18:19], v12, off
	global_store_short_d16_hi v[18:19], v12, off offset:64
	v_mul_f32_e32 v4, v15, v14
	v_mul_f32_e32 v5, v11, v14
	v_mul_f32_e32 v4, v6, v4
	v_mul_f32_e32 v5, v8, v5
	v_cvt_pk_bf16_f32 v11, v4, v5
	global_store_short v[18:19], v11, off offset:128
	global_store_short_d16_hi v[18:19], v11, off offset:192
	v_add_f32_e32 v16, v16, v17
	v_fmamk_f32 v16, v16, 0x3c000000, v254
	s_nop 0
	s_nop 0
	s_nop 0
	s_nop 1
	s_nop 1
	s_nop 0
	v_rsq_f32_e32 v26, v16
	s_nop 0
	v_mul_f32_e32 v17, v24, v26
	v_mul_f32_e32 v24, v25, v26
	v_mul_f32_e32 v17, v7, v17
	v_mul_f32_e32 v24, v9, v24
	v_add_u32_e32 v20, 0x11000, v2
	v_cvt_pk_bf16_f32 v24, v17, v24
	v_mov_b32_e32 v21, v3
	v_lshl_add_u64 v[20:21], v[20:21], 1, s[6:7]
	global_store_short v[20:21], v24, off
	global_store_short_d16_hi v[20:21], v24, off offset:64
	v_mul_f32_e32 v16, v27, v26
	v_mul_f32_e32 v17, v23, v26
	v_mul_f32_e32 v16, v6, v16
	v_mul_f32_e32 v17, v8, v17
	v_cvt_pk_bf16_f32 v23, v16, v17
	global_store_short v[20:21], v23, off offset:128
	global_store_short_d16_hi v[20:21], v23, off offset:192
	ds_read_b32 v11, v10 offset:72
	ds_read2st64_b32 v[4:5], v1 offset0:10 offset1:26
	ds_read_b32 v23, v10 offset:76
	ds_read2st64_b32 v[16:17], v1 offset0:11 offset1:27
	s_waitcnt lgkmcnt(0)
	v_fma_f32 v12, v78, v11, -v4
	v_fma_f32 v13, v94, v11, -v5
	ds_read2st64_b32 v[4:5], v1 offset0:42 offset1:58
	v_mul_f32_e32 v14, v13, v13
	v_fmac_f32_e32 v14, v12, v12
	v_fma_f32 v24, v79, v23, -v16
	v_fma_f32 v25, v95, v23, -v17
	ds_read2st64_b32 v[16:17], v1 offset0:43 offset1:59
	v_mul_f32_e32 v26, v25, v25
	v_fmac_f32_e32 v26, v24, v24
	s_waitcnt lgkmcnt(0)
	v_fma_f32 v15, v110, v11, -v4
	v_fmac_f32_e32 v14, v15, v15
	v_fma_f32 v11, v126, v11, -v5
	v_fmac_f32_e32 v14, v11, v11
	s_nop 1
	v_add_f32_dpp v4, v14, v14 quad_perm:[1,0,3,2] row_mask:0xf bank_mask:0xf
	s_nop 1
	v_add_f32_dpp v4, v4, v4 quad_perm:[2,3,0,1] row_mask:0xf bank_mask:0xf
	s_nop 1
	v_add_f32_dpp v4, v4, v4 row_half_mirror row_mask:0xf bank_mask:0xf
	s_nop 1
	v_add_f32_dpp v4, v4, v4 row_mirror row_mask:0xf bank_mask:0xf
	ds_swizzle_b32 v5, v4 offset:swizzle(SWAP,16)
	v_fma_f32 v27, v111, v23, -v16
	v_fmac_f32_e32 v26, v27, v27
	v_fma_f32 v23, v127, v23, -v17
	v_fmac_f32_e32 v26, v23, v23
	s_nop 1
	v_add_f32_dpp v16, v26, v26 quad_perm:[1,0,3,2] row_mask:0xf bank_mask:0xf
	s_nop 1
	v_add_f32_dpp v16, v16, v16 quad_perm:[2,3,0,1] row_mask:0xf bank_mask:0xf
	s_nop 1
	v_add_f32_dpp v16, v16, v16 row_half_mirror row_mask:0xf bank_mask:0xf
	s_nop 1
	v_add_f32_dpp v16, v16, v16 row_mirror row_mask:0xf bank_mask:0xf
	ds_swizzle_b32 v17, v16 offset:swizzle(SWAP,16)
	s_waitcnt lgkmcnt(0)
	v_add_f32_e32 v4, v4, v5
	v_fmamk_f32 v4, v4, 0x3c000000, v254
	s_nop 0
	s_nop 0
	s_nop 0
	s_nop 1
	s_nop 1
	s_nop 0
	v_rsq_f32_e32 v14, v4
	s_nop 0
	v_mul_f32_e32 v5, v12, v14
	v_mul_f32_e32 v12, v13, v14
	v_mul_f32_e32 v5, v7, v5
	v_mul_f32_e32 v12, v9, v12
	v_add_u32_e32 v18, 0x12000, v2
	v_cvt_pk_bf16_f32 v12, v5, v12
	v_mov_b32_e32 v19, v3
	v_lshl_add_u64 v[18:19], v[18:19], 1, s[6:7]
	global_store_short v[18:19], v12, off
	global_store_short_d16_hi v[18:19], v12, off offset:64
	v_mul_f32_e32 v4, v15, v14
	v_mul_f32_e32 v5, v11, v14
	v_mul_f32_e32 v4, v6, v4
	v_mul_f32_e32 v5, v8, v5
	v_cvt_pk_bf16_f32 v11, v4, v5
	global_store_short v[18:19], v11, off offset:128
	global_store_short_d16_hi v[18:19], v11, off offset:192
	v_add_f32_e32 v16, v16, v17
	v_fmamk_f32 v16, v16, 0x3c000000, v254
	s_nop 0
	s_nop 0
	s_nop 0
	s_nop 1
	s_nop 1
	s_nop 0
	v_rsq_f32_e32 v26, v16
	s_nop 0
	v_mul_f32_e32 v17, v24, v26
	v_mul_f32_e32 v24, v25, v26
	v_mul_f32_e32 v17, v7, v17
	v_mul_f32_e32 v24, v9, v24
	v_add_u32_e32 v20, 0x13000, v2
	v_cvt_pk_bf16_f32 v24, v17, v24
	v_mov_b32_e32 v21, v3
	v_lshl_add_u64 v[20:21], v[20:21], 1, s[6:7]
	global_store_short v[20:21], v24, off
	global_store_short_d16_hi v[20:21], v24, off offset:64
	v_mul_f32_e32 v16, v27, v26
	v_mul_f32_e32 v17, v23, v26
	v_mul_f32_e32 v16, v6, v16
	v_mul_f32_e32 v17, v8, v17
	v_cvt_pk_bf16_f32 v23, v16, v17
	global_store_short v[20:21], v23, off offset:128
	global_store_short_d16_hi v[20:21], v23, off offset:192
	ds_read_b32 v11, v10 offset:96
	ds_read2st64_b32 v[4:5], v1 offset0:12 offset1:28
	ds_read_b32 v23, v10 offset:100
	ds_read2st64_b32 v[16:17], v1 offset0:13 offset1:29
	s_waitcnt lgkmcnt(0)
	v_fma_f32 v12, v80, v11, -v4
	v_fma_f32 v13, v96, v11, -v5
	ds_read2st64_b32 v[4:5], v1 offset0:44 offset1:60
	v_mul_f32_e32 v14, v13, v13
	v_fmac_f32_e32 v14, v12, v12
	v_fma_f32 v24, v81, v23, -v16
	v_fma_f32 v25, v97, v23, -v17
	ds_read2st64_b32 v[16:17], v1 offset0:45 offset1:61
	v_mul_f32_e32 v26, v25, v25
	v_fmac_f32_e32 v26, v24, v24
	s_waitcnt lgkmcnt(0)
	v_fma_f32 v15, v112, v11, -v4
	v_fmac_f32_e32 v14, v15, v15
	v_fma_f32 v11, v128, v11, -v5
	v_fmac_f32_e32 v14, v11, v11
	s_nop 1
	v_add_f32_dpp v4, v14, v14 quad_perm:[1,0,3,2] row_mask:0xf bank_mask:0xf
	s_nop 1
	v_add_f32_dpp v4, v4, v4 quad_perm:[2,3,0,1] row_mask:0xf bank_mask:0xf
	s_nop 1
	v_add_f32_dpp v4, v4, v4 row_half_mirror row_mask:0xf bank_mask:0xf
	s_nop 1
	v_add_f32_dpp v4, v4, v4 row_mirror row_mask:0xf bank_mask:0xf
	ds_swizzle_b32 v5, v4 offset:swizzle(SWAP,16)
	v_fma_f32 v27, v113, v23, -v16
	v_fmac_f32_e32 v26, v27, v27
	v_fma_f32 v23, v129, v23, -v17
	v_fmac_f32_e32 v26, v23, v23
	s_nop 1
	v_add_f32_dpp v16, v26, v26 quad_perm:[1,0,3,2] row_mask:0xf bank_mask:0xf
	s_nop 1
	v_add_f32_dpp v16, v16, v16 quad_perm:[2,3,0,1] row_mask:0xf bank_mask:0xf
	s_nop 1
	v_add_f32_dpp v16, v16, v16 row_half_mirror row_mask:0xf bank_mask:0xf
	s_nop 1
	v_add_f32_dpp v16, v16, v16 row_mirror row_mask:0xf bank_mask:0xf
	ds_swizzle_b32 v17, v16 offset:swizzle(SWAP,16)
	s_waitcnt lgkmcnt(0)
	v_add_f32_e32 v4, v4, v5
	v_fmamk_f32 v4, v4, 0x3c000000, v254
	s_nop 0
	s_nop 0
	s_nop 0
	s_nop 1
	s_nop 1
	s_nop 0
	v_rsq_f32_e32 v14, v4
	s_nop 0
	v_mul_f32_e32 v5, v12, v14
	v_mul_f32_e32 v12, v13, v14
	v_mul_f32_e32 v5, v7, v5
	v_mul_f32_e32 v12, v9, v12
	v_add_u32_e32 v18, 0x18000, v2
	v_cvt_pk_bf16_f32 v12, v5, v12
	v_mov_b32_e32 v19, v3
	v_lshl_add_u64 v[18:19], v[18:19], 1, s[6:7]
	global_store_short v[18:19], v12, off
	global_store_short_d16_hi v[18:19], v12, off offset:64
	v_mul_f32_e32 v4, v15, v14
	v_mul_f32_e32 v5, v11, v14
	v_mul_f32_e32 v4, v6, v4
	v_mul_f32_e32 v5, v8, v5
	v_cvt_pk_bf16_f32 v11, v4, v5
	global_store_short v[18:19], v11, off offset:128
	global_store_short_d16_hi v[18:19], v11, off offset:192
	v_add_f32_e32 v16, v16, v17
	v_fmamk_f32 v16, v16, 0x3c000000, v254
	s_nop 0
	s_nop 0
	s_nop 0
	s_nop 1
	s_nop 1
	s_nop 0
	v_rsq_f32_e32 v26, v16
	s_nop 0
	v_mul_f32_e32 v17, v24, v26
	v_mul_f32_e32 v24, v25, v26
	v_mul_f32_e32 v17, v7, v17
	v_mul_f32_e32 v24, v9, v24
	v_add_u32_e32 v20, 0x19000, v2
	v_cvt_pk_bf16_f32 v24, v17, v24
	v_mov_b32_e32 v21, v3
	v_lshl_add_u64 v[20:21], v[20:21], 1, s[6:7]
	global_store_short v[20:21], v24, off
	global_store_short_d16_hi v[20:21], v24, off offset:64
	v_mul_f32_e32 v16, v27, v26
	v_mul_f32_e32 v17, v23, v26
	v_mul_f32_e32 v16, v6, v16
	v_mul_f32_e32 v17, v8, v17
	v_cvt_pk_bf16_f32 v23, v16, v17
	global_store_short v[20:21], v23, off offset:128
	global_store_short_d16_hi v[20:21], v23, off offset:192
	ds_read_b32 v11, v10 offset:104
	ds_read2st64_b32 v[4:5], v1 offset0:14 offset1:30
	s_waitcnt lgkmcnt(0)
	v_fma_f32 v12, v82, v11, -v4
	v_fma_f32 v13, v98, v11, -v5
	ds_read2st64_b32 v[4:5], v1 offset0:46 offset1:62
	v_mul_f32_e32 v14, v13, v13
	v_fmac_f32_e32 v14, v12, v12
	s_waitcnt lgkmcnt(0)
	v_fma_f32 v15, v114, v11, -v4
	v_fmac_f32_e32 v14, v15, v15
	v_fma_f32 v11, v130, v11, -v5
	v_fmac_f32_e32 v14, v11, v11
	s_nop 1
	v_add_f32_dpp v4, v14, v14 quad_perm:[1,0,3,2] row_mask:0xf bank_mask:0xf
	s_nop 1
	v_add_f32_dpp v4, v4, v4 quad_perm:[2,3,0,1] row_mask:0xf bank_mask:0xf
	s_nop 1
	v_add_f32_dpp v4, v4, v4 row_half_mirror row_mask:0xf bank_mask:0xf
	s_nop 1
	v_add_f32_dpp v4, v4, v4 row_mirror row_mask:0xf bank_mask:0xf
	ds_swizzle_b32 v5, v4 offset:swizzle(SWAP,16)
	s_waitcnt lgkmcnt(0)
	v_add_f32_e32 v4, v4, v5
	v_fmamk_f32 v4, v4, 0x3c000000, v254
	s_nop 0
	s_nop 0
	s_nop 0
	s_nop 1
	s_nop 1
	s_nop 0
	v_rsq_f32_e32 v14, v4
	s_nop 0
	v_mul_f32_e32 v5, v12, v14
	v_mul_f32_e32 v12, v13, v14
	v_mul_f32_e32 v5, v7, v5
	v_mul_f32_e32 v12, v9, v12
	v_add_u32_e32 v18, 0x1a000, v2
	v_cvt_pk_bf16_f32 v12, v5, v12
	v_mov_b32_e32 v19, v3
	v_lshl_add_u64 v[18:19], v[18:19], 1, s[6:7]
	global_store_short v[18:19], v12, off
	global_store_short_d16_hi v[18:19], v12, off offset:64
	v_mul_f32_e32 v4, v15, v14
	v_mul_f32_e32 v5, v11, v14
	v_mul_f32_e32 v4, v6, v4
	v_mul_f32_e32 v5, v8, v5
	v_cvt_pk_bf16_f32 v11, v4, v5
	global_store_short v[18:19], v11, off offset:128
	global_store_short_d16_hi v[18:19], v11, off offset:192
	ds_read_b32 v10, v10 offset:108
	ds_read2st64_b32 v[4:5], v1 offset0:15 offset1:31
	s_waitcnt lgkmcnt(0)
	v_fma_f32 v11, v83, v10, -v4
	v_fma_f32 v12, v99, v10, -v5
	ds_read2st64_b32 v[4:5], v1 offset0:47 offset1:63
	v_mul_f32_e32 v13, v12, v12
	v_fmac_f32_e32 v13, v11, v11
	s_waitcnt lgkmcnt(0)
	v_fma_f32 v1, v115, v10, -v4
	v_fmac_f32_e32 v13, v1, v1
	v_fma_f32 v10, v131, v10, -v5
	v_fmac_f32_e32 v13, v10, v10
	s_nop 1
	v_add_f32_dpp v4, v13, v13 quad_perm:[1,0,3,2] row_mask:0xf bank_mask:0xf
	s_nop 1
	v_add_f32_dpp v4, v4, v4 quad_perm:[2,3,0,1] row_mask:0xf bank_mask:0xf
	s_nop 1
	v_add_f32_dpp v4, v4, v4 row_half_mirror row_mask:0xf bank_mask:0xf
	s_nop 1
	v_add_f32_dpp v4, v4, v4 row_mirror row_mask:0xf bank_mask:0xf
	ds_swizzle_b32 v5, v4 offset:swizzle(SWAP,16)
	s_waitcnt lgkmcnt(0)
	v_add_f32_e32 v4, v4, v5
	v_fmamk_f32 v4, v4, 0x3c000000, v254
	s_nop 0
	s_nop 0
	s_nop 0
	s_nop 1
	s_nop 1
	s_nop 0
	v_rsq_f32_e32 v13, v4
	s_nop 0
	v_mul_f32_e32 v5, v11, v13
	v_mul_f32_e32 v5, v7, v5
	v_mul_f32_e32 v7, v12, v13
	v_mul_f32_e32 v7, v9, v7
	v_add_u32_e32 v4, 0x1b000, v2
	v_cvt_pk_bf16_f32 v7, v5, v7
	v_mov_b32_e32 v5, v3
	v_lshl_add_u64 v[4:5], v[4:5], 1, s[6:7]
	global_store_short v[4:5], v7, off
	v_add_u32_e32 v4, 0x1b020, v2
	v_mov_b32_e32 v5, v3
	v_lshl_add_u64 v[4:5], v[4:5], 1, s[6:7]
	global_store_short_d16_hi v[4:5], v7, off
	v_mul_f32_e32 v1, v1, v13
	v_mul_f32_e32 v4, v10, v13
	v_mul_f32_e32 v1, v6, v1
	v_mul_f32_e32 v4, v8, v4
	v_cvt_pk_bf16_f32 v1, v1, v4
	v_add_u32_e32 v4, 0x1b040, v2
	v_mov_b32_e32 v5, v3
	v_lshl_add_u64 v[4:5], v[4:5], 1, s[6:7]
	v_add_u32_e32 v2, 0x1b060, v2
	global_store_short v[4:5], v1, off
	v_lshl_add_u64 v[4:5], v[2:3], 1, s[6:7]
	global_store_short_d16_hi v[4:5], v1, off

.LBB0_1426:
	s_or_b64 exec, exec, s[4:5]
	s_waitcnt lgkmcnt(0)
	v_lshlrev_b32_e32 v68, 2, v1
	global_load_dword v248, v68, s[0:1]
	global_load_dword v249, v68, s[0:1] offset:128
	global_load_dword v250, v68, s[0:1] offset:256
	global_load_dword v251, v68, s[0:1] offset:384
	s_or_b32 s24, s24, s35
	s_lshl_b64 s[4:5], s[24:25], 13
	s_add_u32 s6, s86, s4
	s_addc_u32 s7, s87, s5
	s_lshl_b64 s[4:5], s[46:47], 1
	s_add_u32 s6, s6, s4
	s_addc_u32 s7, s7, s5
	s_waitcnt vmcnt(0)
	v_mul_f32_e32 v72, v164, v248
	v_mul_f32_e32 v74, v164, v249
	v_mul_f32_e32 v71, v164, v250
	v_mul_f32_e32 v73, v164, v251
	v_lshl_or_b32 v68, v2, 14, v1
	v_lshl_add_u32 v1, v2, 4, s34
	ds_read_b32 v2, v1
	ds_read2st64_b32 v[76:77], v70 offset1:16
	s_waitcnt lgkmcnt(0)
	v_fma_f32 v52, v52, v2, -v76
	v_fma_f32 v36, v36, v2, -v77
	ds_read2st64_b32 v[76:77], v70 offset0:32 offset1:48
	v_mul_f32_e32 v69, v36, v36
	v_fmac_f32_e32 v69, v52, v52
	s_waitcnt lgkmcnt(0)
	v_fma_f32 v20, v20, v2, -v76
	v_fmac_f32_e32 v69, v20, v20
	v_fma_f32 v2, v4, v2, -v77
	v_fmac_f32_e32 v69, v2, v2
	s_nop 1
	v_add_f32_dpp v4, v69, v69 quad_perm:[1,0,3,2] row_mask:0xf bank_mask:0xf
	s_nop 1
	v_add_f32_dpp v4, v4, v4 quad_perm:[2,3,0,1] row_mask:0xf bank_mask:0xf
	s_nop 1
	v_add_f32_dpp v4, v4, v4 row_half_mirror row_mask:0xf bank_mask:0xf
	s_nop 1
	v_add_f32_dpp v4, v4, v4 row_mirror row_mask:0xf bank_mask:0xf
	ds_swizzle_b32 v69, v4 offset:swizzle(SWAP,16)
	s_waitcnt lgkmcnt(0)
	v_add_f32_e32 v4, v4, v69
	v_fmamk_f32 v4, v4, 0x3c000000, v254
	v_cmp_gt_f32_e32 vcc, s90, v4
	v_mul_f32_e32 v69, 0x4f800000, v4
	s_nop 0
	v_cndmask_b32_e32 v4, v4, v69, vcc
	v_sqrt_f32_e32 v69, v4
	s_nop 0
	v_add_u32_e32 v75, -1, v69
	v_fma_f32 v76, -v75, v69, v4
	v_cmp_ge_f32_e64 s[4:5], 0, v76
	v_add_u32_e32 v76, 1, v69
	s_nop 0
	v_cndmask_b32_e64 v75, v69, v75, s[4:5]
	v_fma_f32 v69, -v76, v69, v4
	v_cmp_lt_f32_e64 s[4:5], 0, v69
	s_nop 1
	v_cndmask_b32_e64 v69, v75, v76, s[4:5]
	v_mul_f32_e32 v75, 0x37800000, v69
	v_cndmask_b32_e32 v69, v69, v75, vcc
	v_cmp_class_f32_e32 vcc, v4, v209
	s_nop 1
	v_cndmask_b32_e32 v4, v69, v4, vcc
	v_div_scale_f32 v69, s[4:5], v4, v4, 1.0
	v_rcp_f32_e32 v75, v69
	s_nop 0
	v_fma_f32 v76, -v69, v75, 1.0
	v_fmac_f32_e32 v75, v76, v75
	v_div_scale_f32 v76, vcc, 1.0, v4, 1.0
	v_mul_f32_e32 v77, v76, v75
	v_fma_f32 v78, -v69, v77, v76
	v_fmac_f32_e32 v77, v78, v75
	v_fma_f32 v69, -v69, v77, v76
	v_div_fmas_f32 v69, v69, v75, v77
	v_div_fixup_f32 v4, v69, v4, 1.0
	v_mul_f32_e32 v36, v36, v4
	v_mov_b32_e32 v69, v3
	v_mul_f32_e32 v52, v52, v4
	v_mul_f32_e32 v36, v74, v36
	v_lshl_add_u64 v[76:77], v[68:69], 1, s[6:7]
	v_mul_f32_e32 v52, v72, v52
	v_cvt_pk_bf16_f32 v36, v52, v36
	global_store_short v[76:77], v36, off
	v_add_u32_e32 v76, 32, v68
	v_mov_b32_e32 v77, v3
	v_lshl_add_u64 v[76:77], v[76:77], 1, s[6:7]
	global_store_short_d16_hi v[76:77], v36, off
	v_mul_f32_e32 v2, v2, v4
	v_add_u32_e32 v76, 64, v68
	v_mov_b32_e32 v77, v3
	v_mul_f32_e32 v20, v20, v4
	v_mul_f32_e32 v2, v73, v2
	v_lshl_add_u64 v[76:77], v[76:77], 1, s[6:7]
	v_mul_f32_e32 v20, v71, v20
	v_cvt_pk_bf16_f32 v2, v20, v2
	global_store_short v[76:77], v2, off
	v_add_u32_e32 v76, 0x60, v68
	v_mov_b32_e32 v77, v3
	v_lshl_add_u64 v[76:77], v[76:77], 1, s[6:7]
	global_store_short_d16_hi v[76:77], v2, off
	ds_read_b32 v2, v1 offset:4
	ds_read2st64_b32 v[76:77], v70 offset0:1 offset1:17
	s_waitcnt lgkmcnt(0)
	v_fma_f32 v52, v37, v2, -v77
	ds_read2st64_b32 v[36:37], v70 offset0:33 offset1:49
	v_fma_f32 v20, v53, v2, -v76
	v_mul_f32_e32 v4, v52, v52
	v_fmac_f32_e32 v4, v20, v20
	s_waitcnt lgkmcnt(0)
	v_fma_f32 v21, v21, v2, -v36
	v_fmac_f32_e32 v4, v21, v21
	v_fma_f32 v2, v5, v2, -v37
	v_fmac_f32_e32 v4, v2, v2
	ds_swizzle_b32 v5, v4 offset:swizzle(SWAP,1)
	s_waitcnt lgkmcnt(0)
	v_add_f32_e32 v4, v4, v5
	ds_swizzle_b32 v5, v4 offset:swizzle(SWAP,2)
	s_waitcnt lgkmcnt(0)
	v_add_f32_e32 v4, v4, v5
	ds_swizzle_b32 v5, v4 offset:swizzle(SWAP,4)
	s_waitcnt lgkmcnt(0)
	v_add_f32_e32 v4, v4, v5
	ds_swizzle_b32 v5, v4 offset:swizzle(SWAP,8)
	s_waitcnt lgkmcnt(0)
	v_add_f32_e32 v4, v4, v5
	ds_swizzle_b32 v5, v4 offset:swizzle(SWAP,16)
	s_waitcnt lgkmcnt(0)
	v_add_f32_e32 v4, v4, v5
	v_fmamk_f32 v4, v4, 0x3c000000, v254
	v_cmp_gt_f32_e32 vcc, s90, v4
	v_mul_f32_e32 v5, 0x4f800000, v4
	s_nop 0
	v_cndmask_b32_e32 v4, v4, v5, vcc
	v_sqrt_f32_e32 v5, v4
	s_nop 0
	v_add_u32_e32 v36, -1, v5
	v_fma_f32 v37, -v36, v5, v4
	v_cmp_ge_f32_e64 s[4:5], 0, v37
	v_add_u32_e32 v37, 1, v5
	s_nop 0
	v_cndmask_b32_e64 v36, v5, v36, s[4:5]
	v_fma_f32 v5, -v37, v5, v4
	v_cmp_lt_f32_e64 s[4:5], 0, v5
	s_nop 1
	v_cndmask_b32_e64 v5, v36, v37, s[4:5]
	v_mul_f32_e32 v36, 0x37800000, v5
	v_cndmask_b32_e32 v5, v5, v36, vcc
	v_cmp_class_f32_e32 vcc, v4, v209
	s_nop 1
	v_cndmask_b32_e32 v4, v5, v4, vcc
	v_div_scale_f32 v5, s[4:5], v4, v4, 1.0
	v_rcp_f32_e32 v36, v5
	s_nop 0
	v_fma_f32 v37, -v5, v36, 1.0
	v_fmac_f32_e32 v36, v37, v36
	v_div_scale_f32 v37, vcc, 1.0, v4, 1.0
	v_mul_f32_e32 v53, v37, v36
	v_fma_f32 v69, -v5, v53, v37
	v_fmac_f32_e32 v53, v69, v36
	v_fma_f32 v5, -v5, v53, v37
	v_div_fmas_f32 v5, v5, v36, v53
	v_div_fixup_f32 v36, v5, v4, 1.0
	v_mul_f32_e32 v5, v20, v36
	v_mul_f32_e32 v20, v52, v36
	v_mul_f32_e32 v5, v72, v5
	v_mul_f32_e32 v20, v74, v20
	v_add_u32_e32 v94, 0x1000, v68
	v_cvt_pk_bf16_f32 v20, v5, v20
	v_mov_b32_e32 v95, v3
	v_lshl_add_u64 v[94:95], v[94:95], 1, s[6:7]
	global_store_short v[94:95], v20, off
	global_store_short_d16_hi v[94:95], v20, off offset:64
	v_mul_f32_e32 v4, v21, v36
	v_mul_f32_e32 v2, v2, v36
	v_mul_f32_e32 v4, v71, v4
	v_mul_f32_e32 v2, v73, v2
	v_cvt_pk_bf16_f32 v2, v4, v2
	global_store_short v[94:95], v2, off offset:128
	global_store_short_d16_hi v[94:95], v2, off offset:192
	ds_read_b32 v2, v1 offset:8
	ds_read2st64_b32 v[4:5], v70 offset0:2 offset1:18
	s_waitcnt lgkmcnt(0)
	v_fma_f32 v20, v54, v2, -v4
	v_fma_f32 v21, v38, v2, -v5
	ds_read2st64_b32 v[4:5], v70 offset0:34 offset1:50
	v_mul_f32_e32 v36, v21, v21
	v_fmac_f32_e32 v36, v20, v20
	s_waitcnt lgkmcnt(0)
	v_fma_f32 v22, v22, v2, -v4
	v_fmac_f32_e32 v36, v22, v22
	v_fma_f32 v2, v6, v2, -v5
	v_fmac_f32_e32 v36, v2, v2
	s_nop 1
	v_add_f32_dpp v4, v36, v36 quad_perm:[1,0,3,2] row_mask:0xf bank_mask:0xf
	s_nop 1
	v_add_f32_dpp v4, v4, v4 quad_perm:[2,3,0,1] row_mask:0xf bank_mask:0xf
	s_nop 1
	v_add_f32_dpp v4, v4, v4 row_half_mirror row_mask:0xf bank_mask:0xf
	s_nop 1
	v_add_f32_dpp v4, v4, v4 row_mirror row_mask:0xf bank_mask:0xf
	ds_swizzle_b32 v5, v4 offset:swizzle(SWAP,16)
	s_waitcnt lgkmcnt(0)
	v_add_f32_e32 v4, v4, v5
	v_fmamk_f32 v4, v4, 0x3c000000, v254
	s_nop 0
	s_nop 0
	s_nop 0
	s_nop 1
	s_nop 1
	s_nop 0
	v_rsq_f32_e32 v6, v4
	s_nop 0
	v_mul_f32_e32 v5, v20, v6
	v_mul_f32_e32 v20, v21, v6
	v_mul_f32_e32 v5, v72, v5
	v_mul_f32_e32 v20, v74, v20
	v_add_u32_e32 v92, 0x2000, v68
	v_cvt_pk_bf16_f32 v20, v5, v20
	v_mov_b32_e32 v93, v3
	v_lshl_add_u64 v[92:93], v[92:93], 1, s[6:7]
	global_store_short v[92:93], v20, off
	global_store_short_d16_hi v[92:93], v20, off offset:64
	v_mul_f32_e32 v4, v22, v6
	v_mul_f32_e32 v2, v2, v6
	v_mul_f32_e32 v4, v71, v4
	v_mul_f32_e32 v2, v73, v2
	v_cvt_pk_bf16_f32 v2, v4, v2
	global_store_short v[92:93], v2, off offset:128
	global_store_short_d16_hi v[92:93], v2, off offset:192
	ds_read_b32 v2, v1 offset:12
	ds_read2st64_b32 v[4:5], v70 offset0:3 offset1:19
	s_waitcnt lgkmcnt(0)
	v_fma_f32 v6, v55, v2, -v4
	v_fma_f32 v20, v39, v2, -v5
	ds_read2st64_b32 v[4:5], v70 offset0:35 offset1:51
	v_mul_f32_e32 v21, v20, v20
	v_fmac_f32_e32 v21, v6, v6
	s_waitcnt lgkmcnt(0)
	v_fma_f32 v22, v23, v2, -v4
	v_fmac_f32_e32 v21, v22, v22
	v_fma_f32 v2, v7, v2, -v5
	v_fmac_f32_e32 v21, v2, v2
	s_nop 1
	v_add_f32_dpp v4, v21, v21 quad_perm:[1,0,3,2] row_mask:0xf bank_mask:0xf
	s_nop 1
	v_add_f32_dpp v4, v4, v4 quad_perm:[2,3,0,1] row_mask:0xf bank_mask:0xf
	s_nop 1
	v_add_f32_dpp v4, v4, v4 row_half_mirror row_mask:0xf bank_mask:0xf
	s_nop 1
	v_add_f32_dpp v4, v4, v4 row_mirror row_mask:0xf bank_mask:0xf
	ds_swizzle_b32 v5, v4 offset:swizzle(SWAP,16)
	s_waitcnt lgkmcnt(0)
	v_add_f32_e32 v4, v4, v5
	v_fmamk_f32 v4, v4, 0x3c000000, v254
	s_nop 0
	s_nop 0
	s_nop 0
	s_nop 1
	s_nop 1
	s_nop 0
	v_rsq_f32_e32 v7, v4
	s_nop 0
	v_mul_f32_e32 v5, v6, v7
	v_mul_f32_e32 v6, v20, v7
	v_mul_f32_e32 v5, v72, v5
	v_mul_f32_e32 v6, v74, v6
	v_add_u32_e32 v94, 0x3000, v68
	v_cvt_pk_bf16_f32 v6, v5, v6
	v_mov_b32_e32 v95, v3
	v_lshl_add_u64 v[94:95], v[94:95], 1, s[6:7]
	global_store_short v[94:95], v6, off
	global_store_short_d16_hi v[94:95], v6, off offset:64
	v_mul_f32_e32 v4, v22, v7
	v_mul_f32_e32 v2, v2, v7
	v_mul_f32_e32 v4, v71, v4
	v_mul_f32_e32 v2, v73, v2
	v_cvt_pk_bf16_f32 v2, v4, v2
	global_store_short v[94:95], v2, off offset:128
	global_store_short_d16_hi v[94:95], v2, off offset:192
	ds_read_b32 v2, v1 offset:32
	ds_read2st64_b32 v[4:5], v70 offset0:4 offset1:20
	s_waitcnt lgkmcnt(0)
	v_fma_f32 v6, v56, v2, -v4
	v_fma_f32 v7, v40, v2, -v5
	ds_read2st64_b32 v[4:5], v70 offset0:36 offset1:52
	v_mul_f32_e32 v20, v7, v7
	v_fmac_f32_e32 v20, v6, v6
	s_waitcnt lgkmcnt(0)
	v_fma_f32 v21, v24, v2, -v4
	v_fmac_f32_e32 v20, v21, v21
	v_fma_f32 v2, v8, v2, -v5
	v_fmac_f32_e32 v20, v2, v2
	s_nop 1
	v_add_f32_dpp v4, v20, v20 quad_perm:[1,0,3,2] row_mask:0xf bank_mask:0xf
	s_nop 1
	v_add_f32_dpp v4, v4, v4 quad_perm:[2,3,0,1] row_mask:0xf bank_mask:0xf
	s_nop 1
	v_add_f32_dpp v4, v4, v4 row_half_mirror row_mask:0xf bank_mask:0xf
	s_nop 1
	v_add_f32_dpp v4, v4, v4 row_mirror row_mask:0xf bank_mask:0xf
	ds_swizzle_b32 v5, v4 offset:swizzle(SWAP,16)
	s_waitcnt lgkmcnt(0)
	v_add_f32_e32 v4, v4, v5
	v_fmamk_f32 v4, v4, 0x3c000000, v254
	s_nop 0
	s_nop 0
	s_nop 0
	s_nop 1
	s_nop 1
	s_nop 0
	v_rsq_f32_e32 v8, v4
	s_nop 0
	v_mul_f32_e32 v5, v6, v8
	v_mul_f32_e32 v6, v7, v8
	v_mul_f32_e32 v5, v72, v5
	v_mul_f32_e32 v6, v74, v6
	v_add_u32_e32 v92, 0x8000, v68
	v_cvt_pk_bf16_f32 v6, v5, v6
	v_mov_b32_e32 v93, v3
	v_lshl_add_u64 v[92:93], v[92:93], 1, s[6:7]
	global_store_short v[92:93], v6, off
	global_store_short_d16_hi v[92:93], v6, off offset:64
	v_mul_f32_e32 v4, v21, v8
	v_mul_f32_e32 v2, v2, v8
	v_mul_f32_e32 v4, v71, v4
	v_mul_f32_e32 v2, v73, v2
	v_cvt_pk_bf16_f32 v2, v4, v2
	global_store_short v[92:93], v2, off offset:128
	global_store_short_d16_hi v[92:93], v2, off offset:192
	ds_read_b32 v2, v1 offset:36
	ds_read2st64_b32 v[4:5], v70 offset0:5 offset1:21
	s_waitcnt lgkmcnt(0)
	v_fma_f32 v6, v57, v2, -v4
	v_fma_f32 v7, v41, v2, -v5
	ds_read2st64_b32 v[4:5], v70 offset0:37 offset1:53
	v_mul_f32_e32 v8, v7, v7
	v_fmac_f32_e32 v8, v6, v6
	s_waitcnt lgkmcnt(0)
	v_fma_f32 v20, v25, v2, -v4
	v_fmac_f32_e32 v8, v20, v20
	v_fma_f32 v2, v9, v2, -v5
	v_fmac_f32_e32 v8, v2, v2
	s_nop 1
	v_add_f32_dpp v4, v8, v8 quad_perm:[1,0,3,2] row_mask:0xf bank_mask:0xf
	s_nop 1
	v_add_f32_dpp v4, v4, v4 quad_perm:[2,3,0,1] row_mask:0xf bank_mask:0xf
	s_nop 1
	v_add_f32_dpp v4, v4, v4 row_half_mirror row_mask:0xf bank_mask:0xf
	s_nop 1
	v_add_f32_dpp v4, v4, v4 row_mirror row_mask:0xf bank_mask:0xf
	ds_swizzle_b32 v5, v4 offset:swizzle(SWAP,16)
	s_waitcnt lgkmcnt(0)
	v_add_f32_e32 v4, v4, v5
	v_fmamk_f32 v4, v4, 0x3c000000, v254
	s_nop 0
	s_nop 0
	s_nop 0
	s_nop 1
	s_nop 1
	s_nop 0
	v_rsq_f32_e32 v8, v4
	s_nop 0
	v_mul_f32_e32 v5, v6, v8
	v_mul_f32_e32 v6, v7, v8
	v_mul_f32_e32 v5, v72, v5
	v_mul_f32_e32 v6, v74, v6
	v_add_u32_e32 v94, 0x9000, v68
	v_cvt_pk_bf16_f32 v6, v5, v6
	v_mov_b32_e32 v95, v3
	v_lshl_add_u64 v[94:95], v[94:95], 1, s[6:7]
	global_store_short v[94:95], v6, off
	global_store_short_d16_hi v[94:95], v6, off offset:64
	v_mul_f32_e32 v4, v20, v8
	v_mul_f32_e32 v2, v2, v8
	v_mul_f32_e32 v4, v71, v4
	v_mul_f32_e32 v2, v73, v2
	v_cvt_pk_bf16_f32 v2, v4, v2
	global_store_short v[94:95], v2, off offset:128
	global_store_short_d16_hi v[94:95], v2, off offset:192
	ds_read_b32 v2, v1 offset:40
	ds_read2st64_b32 v[4:5], v70 offset0:6 offset1:22
	ds_read_b32 v84, v1 offset:44
	ds_read2st64_b32 v[86:87], v70 offset0:7 offset1:23
	s_waitcnt lgkmcnt(0)
	v_fma_f32 v6, v58, v2, -v4
	v_fma_f32 v7, v42, v2, -v5
	ds_read2st64_b32 v[4:5], v70 offset0:38 offset1:54
	v_mul_f32_e32 v8, v7, v7
	v_fmac_f32_e32 v8, v6, v6
	v_fma_f32 v88, v59, v84, -v86
	v_fma_f32 v89, v43, v84, -v87
	ds_read2st64_b32 v[86:87], v70 offset0:39 offset1:55
	v_mul_f32_e32 v90, v89, v89
	v_fmac_f32_e32 v90, v88, v88
	s_waitcnt lgkmcnt(0)
	v_fma_f32 v9, v26, v2, -v4
	v_fmac_f32_e32 v8, v9, v9
	v_fma_f32 v2, v10, v2, -v5
	v_fmac_f32_e32 v8, v2, v2
	s_nop 1
	v_add_f32_dpp v4, v8, v8 quad_perm:[1,0,3,2] row_mask:0xf bank_mask:0xf
	s_nop 1
	v_add_f32_dpp v4, v4, v4 quad_perm:[2,3,0,1] row_mask:0xf bank_mask:0xf
	s_nop 1
	v_add_f32_dpp v4, v4, v4 row_half_mirror row_mask:0xf bank_mask:0xf
	s_nop 1
	v_add_f32_dpp v4, v4, v4 row_mirror row_mask:0xf bank_mask:0xf
	ds_swizzle_b32 v5, v4 offset:swizzle(SWAP,16)
	v_fma_f32 v91, v27, v84, -v86
	v_fmac_f32_e32 v90, v91, v91
	v_fma_f32 v84, v11, v84, -v87
	v_fmac_f32_e32 v90, v84, v84
	s_nop 1
	v_add_f32_dpp v86, v90, v90 quad_perm:[1,0,3,2] row_mask:0xf bank_mask:0xf
	s_nop 1
	v_add_f32_dpp v86, v86, v86 quad_perm:[2,3,0,1] row_mask:0xf bank_mask:0xf
	s_nop 1
	v_add_f32_dpp v86, v86, v86 row_half_mirror row_mask:0xf bank_mask:0xf
	s_nop 1
	v_add_f32_dpp v86, v86, v86 row_mirror row_mask:0xf bank_mask:0xf
	ds_swizzle_b32 v87, v86 offset:swizzle(SWAP,16)
	s_waitcnt lgkmcnt(0)
	v_add_f32_e32 v4, v4, v5
	v_fmamk_f32 v4, v4, 0x3c000000, v254
	s_nop 0
	s_nop 0
	s_nop 0
	s_nop 1
	s_nop 1
	s_nop 0
	v_rsq_f32_e32 v8, v4
	s_nop 0
	v_mul_f32_e32 v5, v6, v8
	v_mul_f32_e32 v6, v7, v8
	v_mul_f32_e32 v5, v72, v5
	v_mul_f32_e32 v6, v74, v6
	v_add_u32_e32 v92, 0xa000, v68
	v_cvt_pk_bf16_f32 v6, v5, v6
	v_mov_b32_e32 v93, v3
	v_lshl_add_u64 v[92:93], v[92:93], 1, s[6:7]
	global_store_short v[92:93], v6, off
	global_store_short_d16_hi v[92:93], v6, off offset:64
	v_mul_f32_e32 v4, v9, v8
	v_mul_f32_e32 v2, v2, v8
	v_mul_f32_e32 v4, v71, v4
	v_mul_f32_e32 v2, v73, v2
	v_cvt_pk_bf16_f32 v2, v4, v2
	global_store_short v[92:93], v2, off offset:128
	global_store_short_d16_hi v[92:93], v2, off offset:192
	v_add_f32_e32 v86, v86, v87
	v_fmamk_f32 v86, v86, 0x3c000000, v254
	s_nop 0
	s_nop 0
	s_nop 0
	s_nop 1
	s_nop 1
	s_nop 0
	v_rsq_f32_e32 v90, v86
	s_nop 0
	v_mul_f32_e32 v87, v88, v90
	v_mul_f32_e32 v88, v89, v90
	v_mul_f32_e32 v87, v72, v87
	v_mul_f32_e32 v88, v74, v88
	v_add_u32_e32 v94, 0xb000, v68
	v_cvt_pk_bf16_f32 v88, v87, v88
	v_mov_b32_e32 v95, v3
	v_lshl_add_u64 v[94:95], v[94:95], 1, s[6:7]
	global_store_short v[94:95], v88, off
	global_store_short_d16_hi v[94:95], v88, off offset:64
	v_mul_f32_e32 v86, v91, v90
	v_mul_f32_e32 v84, v84, v90
	v_mul_f32_e32 v86, v71, v86
	v_mul_f32_e32 v84, v73, v84
	v_cvt_pk_bf16_f32 v84, v86, v84
	global_store_short v[94:95], v84, off offset:128
	global_store_short_d16_hi v[94:95], v84, off offset:192
	ds_read_b32 v2, v1 offset:64
	ds_read2st64_b32 v[4:5], v70 offset0:8 offset1:24
	ds_read_b32 v84, v1 offset:68
	ds_read2st64_b32 v[86:87], v70 offset0:9 offset1:25
	s_waitcnt lgkmcnt(0)
	v_fma_f32 v6, v60, v2, -v4
	v_fma_f32 v7, v44, v2, -v5
	ds_read2st64_b32 v[4:5], v70 offset0:40 offset1:56
	v_mul_f32_e32 v8, v7, v7
	v_fmac_f32_e32 v8, v6, v6
	v_fma_f32 v88, v61, v84, -v86
	v_fma_f32 v89, v45, v84, -v87
	ds_read2st64_b32 v[86:87], v70 offset0:41 offset1:57
	v_mul_f32_e32 v90, v89, v89
	v_fmac_f32_e32 v90, v88, v88
	s_waitcnt lgkmcnt(0)
	v_fma_f32 v9, v28, v2, -v4
	v_fmac_f32_e32 v8, v9, v9
	v_fma_f32 v2, v12, v2, -v5
	v_fmac_f32_e32 v8, v2, v2
	s_nop 1
	v_add_f32_dpp v4, v8, v8 quad_perm:[1,0,3,2] row_mask:0xf bank_mask:0xf
	s_nop 1
	v_add_f32_dpp v4, v4, v4 quad_perm:[2,3,0,1] row_mask:0xf bank_mask:0xf
	s_nop 1
	v_add_f32_dpp v4, v4, v4 row_half_mirror row_mask:0xf bank_mask:0xf
	s_nop 1
	v_add_f32_dpp v4, v4, v4 row_mirror row_mask:0xf bank_mask:0xf
	ds_swizzle_b32 v5, v4 offset:swizzle(SWAP,16)
	v_fma_f32 v91, v29, v84, -v86
	v_fmac_f32_e32 v90, v91, v91
	v_fma_f32 v84, v13, v84, -v87
	v_fmac_f32_e32 v90, v84, v84
	s_nop 1
	v_add_f32_dpp v86, v90, v90 quad_perm:[1,0,3,2] row_mask:0xf bank_mask:0xf
	s_nop 1
	v_add_f32_dpp v86, v86, v86 quad_perm:[2,3,0,1] row_mask:0xf bank_mask:0xf
	s_nop 1
	v_add_f32_dpp v86, v86, v86 row_half_mirror row_mask:0xf bank_mask:0xf
	s_nop 1
	v_add_f32_dpp v86, v86, v86 row_mirror row_mask:0xf bank_mask:0xf
	ds_swizzle_b32 v87, v86 offset:swizzle(SWAP,16)
	s_waitcnt lgkmcnt(0)
	v_add_f32_e32 v4, v4, v5
	v_fmamk_f32 v4, v4, 0x3c000000, v254
	s_nop 0
	s_nop 0
	s_nop 0
	s_nop 1
	s_nop 1
	s_nop 0
	v_rsq_f32_e32 v8, v4
	s_nop 0
	v_mul_f32_e32 v5, v6, v8
	v_mul_f32_e32 v6, v7, v8
	v_mul_f32_e32 v5, v72, v5
	v_mul_f32_e32 v6, v74, v6
	v_add_u32_e32 v92, 0x10000, v68
	v_cvt_pk_bf16_f32 v6, v5, v6
	v_mov_b32_e32 v93, v3
	v_lshl_add_u64 v[92:93], v[92:93], 1, s[6:7]
	global_store_short v[92:93], v6, off
	global_store_short_d16_hi v[92:93], v6, off offset:64
	v_mul_f32_e32 v4, v9, v8
	v_mul_f32_e32 v2, v2, v8
	v_mul_f32_e32 v4, v71, v4
	v_mul_f32_e32 v2, v73, v2
	v_cvt_pk_bf16_f32 v2, v4, v2
	global_store_short v[92:93], v2, off offset:128
	global_store_short_d16_hi v[92:93], v2, off offset:192
	v_add_f32_e32 v86, v86, v87
	v_fmamk_f32 v86, v86, 0x3c000000, v254
	s_nop 0
	s_nop 0
	s_nop 0
	s_nop 1
	s_nop 1
	s_nop 0
	v_rsq_f32_e32 v90, v86
	s_nop 0
	v_mul_f32_e32 v87, v88, v90
	v_mul_f32_e32 v88, v89, v90
	v_mul_f32_e32 v87, v72, v87
	v_mul_f32_e32 v88, v74, v88
	v_add_u32_e32 v94, 0x11000, v68
	v_cvt_pk_bf16_f32 v88, v87, v88
	v_mov_b32_e32 v95, v3
	v_lshl_add_u64 v[94:95], v[94:95], 1, s[6:7]
	global_store_short v[94:95], v88, off
	global_store_short_d16_hi v[94:95], v88, off offset:64
	v_mul_f32_e32 v86, v91, v90
	v_mul_f32_e32 v84, v84, v90
	v_mul_f32_e32 v86, v71, v86
	v_mul_f32_e32 v84, v73, v84
	v_cvt_pk_bf16_f32 v84, v86, v84
	global_store_short v[94:95], v84, off offset:128
	global_store_short_d16_hi v[94:95], v84, off offset:192
	ds_read_b32 v2, v1 offset:72
	ds_read2st64_b32 v[4:5], v70 offset0:10 offset1:26
	ds_read_b32 v84, v1 offset:76
	ds_read2st64_b32 v[86:87], v70 offset0:11 offset1:27
	s_waitcnt lgkmcnt(0)
	v_fma_f32 v6, v62, v2, -v4
	v_fma_f32 v7, v46, v2, -v5
	ds_read2st64_b32 v[4:5], v70 offset0:42 offset1:58
	v_mul_f32_e32 v8, v7, v7
	v_fmac_f32_e32 v8, v6, v6
	v_fma_f32 v88, v63, v84, -v86
	v_fma_f32 v89, v47, v84, -v87
	ds_read2st64_b32 v[86:87], v70 offset0:43 offset1:59
	v_mul_f32_e32 v90, v89, v89
	v_fmac_f32_e32 v90, v88, v88
	s_waitcnt lgkmcnt(0)
	v_fma_f32 v9, v30, v2, -v4
	v_fmac_f32_e32 v8, v9, v9
	v_fma_f32 v2, v14, v2, -v5
	v_fmac_f32_e32 v8, v2, v2
	s_nop 1
	v_add_f32_dpp v4, v8, v8 quad_perm:[1,0,3,2] row_mask:0xf bank_mask:0xf
	s_nop 1
	v_add_f32_dpp v4, v4, v4 quad_perm:[2,3,0,1] row_mask:0xf bank_mask:0xf
	s_nop 1
	v_add_f32_dpp v4, v4, v4 row_half_mirror row_mask:0xf bank_mask:0xf
	s_nop 1
	v_add_f32_dpp v4, v4, v4 row_mirror row_mask:0xf bank_mask:0xf
	ds_swizzle_b32 v5, v4 offset:swizzle(SWAP,16)
	v_fma_f32 v91, v31, v84, -v86
	v_fmac_f32_e32 v90, v91, v91
	v_fma_f32 v84, v15, v84, -v87
	v_fmac_f32_e32 v90, v84, v84
	s_nop 1
	v_add_f32_dpp v86, v90, v90 quad_perm:[1,0,3,2] row_mask:0xf bank_mask:0xf
	s_nop 1
	v_add_f32_dpp v86, v86, v86 quad_perm:[2,3,0,1] row_mask:0xf bank_mask:0xf
	s_nop 1
	v_add_f32_dpp v86, v86, v86 row_half_mirror row_mask:0xf bank_mask:0xf
	s_nop 1
	v_add_f32_dpp v86, v86, v86 row_mirror row_mask:0xf bank_mask:0xf
	ds_swizzle_b32 v87, v86 offset:swizzle(SWAP,16)
	s_waitcnt lgkmcnt(0)
	v_add_f32_e32 v4, v4, v5
	v_fmamk_f32 v4, v4, 0x3c000000, v254
	s_nop 0
	s_nop 0
	s_nop 0
	s_nop 1
	s_nop 1
	s_nop 0
	v_rsq_f32_e32 v8, v4
	s_nop 0
	v_mul_f32_e32 v5, v6, v8
	v_mul_f32_e32 v6, v7, v8
	v_mul_f32_e32 v5, v72, v5
	v_mul_f32_e32 v6, v74, v6
	v_add_u32_e32 v92, 0x12000, v68
	v_cvt_pk_bf16_f32 v6, v5, v6
	v_mov_b32_e32 v93, v3
	v_lshl_add_u64 v[92:93], v[92:93], 1, s[6:7]
	global_store_short v[92:93], v6, off
	global_store_short_d16_hi v[92:93], v6, off offset:64
	v_mul_f32_e32 v4, v9, v8
	v_mul_f32_e32 v2, v2, v8
	v_mul_f32_e32 v4, v71, v4
	v_mul_f32_e32 v2, v73, v2
	v_cvt_pk_bf16_f32 v2, v4, v2
	global_store_short v[92:93], v2, off offset:128
	global_store_short_d16_hi v[92:93], v2, off offset:192
	v_add_f32_e32 v86, v86, v87
	v_fmamk_f32 v86, v86, 0x3c000000, v254
	s_nop 0
	s_nop 0
	s_nop 0
	s_nop 1
	s_nop 1
	s_nop 0
	v_rsq_f32_e32 v90, v86
	s_nop 0
	v_mul_f32_e32 v87, v88, v90
	v_mul_f32_e32 v88, v89, v90
	v_mul_f32_e32 v87, v72, v87
	v_mul_f32_e32 v88, v74, v88
	v_add_u32_e32 v94, 0x13000, v68
	v_cvt_pk_bf16_f32 v88, v87, v88
	v_mov_b32_e32 v95, v3
	v_lshl_add_u64 v[94:95], v[94:95], 1, s[6:7]
	global_store_short v[94:95], v88, off
	global_store_short_d16_hi v[94:95], v88, off offset:64
	v_mul_f32_e32 v86, v91, v90
	v_mul_f32_e32 v84, v84, v90
	v_mul_f32_e32 v86, v71, v86
	v_mul_f32_e32 v84, v73, v84
	v_cvt_pk_bf16_f32 v84, v86, v84
	global_store_short v[94:95], v84, off offset:128
	global_store_short_d16_hi v[94:95], v84, off offset:192
	ds_read_b32 v2, v1 offset:96
	ds_read2st64_b32 v[4:5], v70 offset0:12 offset1:28
	ds_read_b32 v84, v1 offset:100
	ds_read2st64_b32 v[86:87], v70 offset0:13 offset1:29
	s_waitcnt lgkmcnt(0)
	v_fma_f32 v6, v64, v2, -v4
	v_fma_f32 v7, v48, v2, -v5
	ds_read2st64_b32 v[4:5], v70 offset0:44 offset1:60
	v_mul_f32_e32 v8, v7, v7
	v_fmac_f32_e32 v8, v6, v6
	v_fma_f32 v88, v65, v84, -v86
	v_fma_f32 v89, v49, v84, -v87
	ds_read2st64_b32 v[86:87], v70 offset0:45 offset1:61
	v_mul_f32_e32 v90, v89, v89
	v_fmac_f32_e32 v90, v88, v88
	s_waitcnt lgkmcnt(0)
	v_fma_f32 v9, v32, v2, -v4
	v_fmac_f32_e32 v8, v9, v9
	v_fma_f32 v2, v16, v2, -v5
	v_fmac_f32_e32 v8, v2, v2
	s_nop 1
	v_add_f32_dpp v4, v8, v8 quad_perm:[1,0,3,2] row_mask:0xf bank_mask:0xf
	s_nop 1
	v_add_f32_dpp v4, v4, v4 quad_perm:[2,3,0,1] row_mask:0xf bank_mask:0xf
	s_nop 1
	v_add_f32_dpp v4, v4, v4 row_half_mirror row_mask:0xf bank_mask:0xf
	s_nop 1
	v_add_f32_dpp v4, v4, v4 row_mirror row_mask:0xf bank_mask:0xf
	ds_swizzle_b32 v5, v4 offset:swizzle(SWAP,16)
	v_fma_f32 v91, v33, v84, -v86
	v_fmac_f32_e32 v90, v91, v91
	v_fma_f32 v84, v17, v84, -v87
	v_fmac_f32_e32 v90, v84, v84
	s_nop 1
	v_add_f32_dpp v86, v90, v90 quad_perm:[1,0,3,2] row_mask:0xf bank_mask:0xf
	s_nop 1
	v_add_f32_dpp v86, v86, v86 quad_perm:[2,3,0,1] row_mask:0xf bank_mask:0xf
	s_nop 1
	v_add_f32_dpp v86, v86, v86 row_half_mirror row_mask:0xf bank_mask:0xf
	s_nop 1
	v_add_f32_dpp v86, v86, v86 row_mirror row_mask:0xf bank_mask:0xf
	ds_swizzle_b32 v87, v86 offset:swizzle(SWAP,16)
	s_waitcnt lgkmcnt(0)
	v_add_f32_e32 v4, v4, v5
	v_fmamk_f32 v4, v4, 0x3c000000, v254
	s_nop 0
	s_nop 0
	s_nop 0
	s_nop 1
	s_nop 1
	s_nop 0
	v_rsq_f32_e32 v8, v4
	s_nop 0
	v_mul_f32_e32 v5, v6, v8
	v_mul_f32_e32 v6, v7, v8
	v_mul_f32_e32 v5, v72, v5
	v_mul_f32_e32 v6, v74, v6
	v_add_u32_e32 v92, 0x18000, v68
	v_cvt_pk_bf16_f32 v6, v5, v6
	v_mov_b32_e32 v93, v3
	v_lshl_add_u64 v[92:93], v[92:93], 1, s[6:7]
	global_store_short v[92:93], v6, off
	global_store_short_d16_hi v[92:93], v6, off offset:64
	v_mul_f32_e32 v4, v9, v8
	v_mul_f32_e32 v2, v2, v8
	v_mul_f32_e32 v4, v71, v4
	v_mul_f32_e32 v2, v73, v2
	v_cvt_pk_bf16_f32 v2, v4, v2
	global_store_short v[92:93], v2, off offset:128
	global_store_short_d16_hi v[92:93], v2, off offset:192
	v_add_f32_e32 v86, v86, v87
	v_fmamk_f32 v86, v86, 0x3c000000, v254
	s_nop 0
	s_nop 0
	s_nop 0
	s_nop 1
	s_nop 1
	s_nop 0
	v_rsq_f32_e32 v90, v86
	s_nop 0
	v_mul_f32_e32 v87, v88, v90
	v_mul_f32_e32 v88, v89, v90
	v_mul_f32_e32 v87, v72, v87
	v_mul_f32_e32 v88, v74, v88
	v_add_u32_e32 v94, 0x19000, v68
	v_cvt_pk_bf16_f32 v88, v87, v88
	v_mov_b32_e32 v95, v3
	v_lshl_add_u64 v[94:95], v[94:95], 1, s[6:7]
	global_store_short v[94:95], v88, off
	global_store_short_d16_hi v[94:95], v88, off offset:64
	v_mul_f32_e32 v86, v91, v90
	v_mul_f32_e32 v84, v84, v90
	v_mul_f32_e32 v86, v71, v86
	v_mul_f32_e32 v84, v73, v84
	v_cvt_pk_bf16_f32 v84, v86, v84
	global_store_short v[94:95], v84, off offset:128
	global_store_short_d16_hi v[94:95], v84, off offset:192
	ds_read_b32 v2, v1 offset:104
	ds_read2st64_b32 v[4:5], v70 offset0:14 offset1:30
	s_waitcnt lgkmcnt(0)
	v_fma_f32 v6, v66, v2, -v4
	v_fma_f32 v7, v50, v2, -v5
	ds_read2st64_b32 v[4:5], v70 offset0:46 offset1:62
	v_mul_f32_e32 v8, v7, v7
	v_fmac_f32_e32 v8, v6, v6
	s_waitcnt lgkmcnt(0)
	v_fma_f32 v9, v34, v2, -v4
	v_fmac_f32_e32 v8, v9, v9
	v_fma_f32 v2, v18, v2, -v5
	v_fmac_f32_e32 v8, v2, v2
	s_nop 1
	v_add_f32_dpp v4, v8, v8 quad_perm:[1,0,3,2] row_mask:0xf bank_mask:0xf
	s_nop 1
	v_add_f32_dpp v4, v4, v4 quad_perm:[2,3,0,1] row_mask:0xf bank_mask:0xf
	s_nop 1
	v_add_f32_dpp v4, v4, v4 row_half_mirror row_mask:0xf bank_mask:0xf
	s_nop 1
	v_add_f32_dpp v4, v4, v4 row_mirror row_mask:0xf bank_mask:0xf
	ds_swizzle_b32 v5, v4 offset:swizzle(SWAP,16)
	s_waitcnt lgkmcnt(0)
	v_add_f32_e32 v4, v4, v5
	v_fmamk_f32 v4, v4, 0x3c000000, v254
	v_cmp_gt_f32_e32 vcc, s90, v4
	v_mul_f32_e32 v5, 0x4f800000, v4
	s_nop 0
	v_cndmask_b32_e32 v4, v4, v5, vcc
	v_sqrt_f32_e32 v5, v4
	s_nop 0
	v_add_u32_e32 v8, -1, v5
	v_fma_f32 v10, -v8, v5, v4
	v_cmp_ge_f32_e64 s[4:5], 0, v10
	v_add_u32_e32 v10, 1, v5
	s_nop 0
	v_cndmask_b32_e64 v8, v5, v8, s[4:5]
	v_fma_f32 v5, -v10, v5, v4
	v_cmp_lt_f32_e64 s[4:5], 0, v5
	s_nop 1
	v_cndmask_b32_e64 v5, v8, v10, s[4:5]
	v_mul_f32_e32 v8, 0x37800000, v5
	v_cndmask_b32_e32 v5, v5, v8, vcc
	v_cmp_class_f32_e32 vcc, v4, v209
	s_nop 1
	v_cndmask_b32_e32 v4, v5, v4, vcc
	v_div_scale_f32 v5, s[4:5], v4, v4, 1.0
	v_rcp_f32_e32 v8, v5
	s_nop 0
	v_fma_f32 v10, -v5, v8, 1.0
	v_fmac_f32_e32 v8, v10, v8
	v_div_scale_f32 v10, vcc, 1.0, v4, 1.0
	v_mul_f32_e32 v11, v10, v8
	v_fma_f32 v12, -v5, v11, v10
	v_fmac_f32_e32 v11, v12, v8
	v_fma_f32 v5, -v5, v11, v10
	v_div_fmas_f32 v5, v5, v8, v11
	v_div_fixup_f32 v8, v5, v4, 1.0
	v_mul_f32_e32 v5, v6, v8
	v_mul_f32_e32 v6, v7, v8
	v_mul_f32_e32 v5, v72, v5
	v_mul_f32_e32 v6, v74, v6
	v_add_u32_e32 v92, 0x1a000, v68
	v_cvt_pk_bf16_f32 v6, v5, v6
	v_mov_b32_e32 v93, v3
	v_lshl_add_u64 v[92:93], v[92:93], 1, s[6:7]
	global_store_short v[92:93], v6, off
	global_store_short_d16_hi v[92:93], v6, off offset:64
	v_mul_f32_e32 v4, v9, v8
	v_mul_f32_e32 v2, v2, v8
	v_mul_f32_e32 v4, v71, v4
	v_mul_f32_e32 v2, v73, v2
	v_cvt_pk_bf16_f32 v2, v4, v2
	global_store_short v[92:93], v2, off offset:128
	global_store_short_d16_hi v[92:93], v2, off offset:192
	ds_read_b32 v1, v1 offset:108
	ds_read2st64_b32 v[4:5], v70 offset0:15 offset1:31
	s_waitcnt lgkmcnt(0)
	v_fma_f32 v2, v67, v1, -v4
	v_fma_f32 v6, v51, v1, -v5
	ds_read2st64_b32 v[4:5], v70 offset0:47 offset1:63
	v_mul_f32_e32 v7, v6, v6
	v_fmac_f32_e32 v7, v2, v2
	s_waitcnt lgkmcnt(0)
	v_fma_f32 v8, v35, v1, -v4
	v_fmac_f32_e32 v7, v8, v8
	v_fma_f32 v1, v19, v1, -v5
	v_fmac_f32_e32 v7, v1, v1
	s_nop 1
	v_add_f32_dpp v4, v7, v7 quad_perm:[1,0,3,2] row_mask:0xf bank_mask:0xf
	s_nop 1
	v_add_f32_dpp v4, v4, v4 quad_perm:[2,3,0,1] row_mask:0xf bank_mask:0xf
	s_nop 1
	v_add_f32_dpp v4, v4, v4 row_half_mirror row_mask:0xf bank_mask:0xf
	s_nop 1
	v_add_f32_dpp v4, v4, v4 row_mirror row_mask:0xf bank_mask:0xf
	ds_swizzle_b32 v5, v4 offset:swizzle(SWAP,16)
	s_waitcnt lgkmcnt(0)
	v_add_f32_e32 v4, v4, v5
	v_fmamk_f32 v4, v4, 0x3c000000, v254
	v_cmp_gt_f32_e32 vcc, s90, v4
	v_mul_f32_e32 v5, 0x4f800000, v4
	s_nop 0
	v_cndmask_b32_e32 v4, v4, v5, vcc
	v_sqrt_f32_e32 v5, v4
	s_nop 0
	v_add_u32_e32 v7, -1, v5
	v_fma_f32 v9, -v7, v5, v4
	v_cmp_ge_f32_e64 s[4:5], 0, v9
	v_add_u32_e32 v9, 1, v5
	s_nop 0
	v_cndmask_b32_e64 v7, v5, v7, s[4:5]
	v_fma_f32 v5, -v9, v5, v4
	v_cmp_lt_f32_e64 s[4:5], 0, v5
	s_nop 1
	v_cndmask_b32_e64 v5, v7, v9, s[4:5]
	v_mul_f32_e32 v7, 0x37800000, v5
	v_cndmask_b32_e32 v5, v5, v7, vcc
	v_cmp_class_f32_e32 vcc, v4, v209
	s_nop 1
	v_cndmask_b32_e32 v4, v5, v4, vcc
	v_div_scale_f32 v5, s[4:5], v4, v4, 1.0
	v_rcp_f32_e32 v7, v5
	s_nop 0
	v_fma_f32 v9, -v5, v7, 1.0
	v_fmac_f32_e32 v7, v9, v7
	v_div_scale_f32 v9, vcc, 1.0, v4, 1.0
	v_mul_f32_e32 v10, v9, v7
	v_fma_f32 v11, -v5, v10, v9
	v_fmac_f32_e32 v10, v11, v7
	v_fma_f32 v5, -v5, v10, v9
	v_div_fmas_f32 v5, v5, v7, v10
	v_div_fixup_f32 v7, v5, v4, 1.0
	v_mul_f32_e32 v2, v2, v7
	v_mul_f32_e32 v5, v6, v7
	v_mul_f32_e32 v2, v72, v2
	v_mul_f32_e32 v5, v74, v5
	v_add_u32_e32 v4, 0x1b000, v68
	v_cvt_pk_bf16_f32 v2, v2, v5
	v_mov_b32_e32 v5, v3
	v_lshl_add_u64 v[4:5], v[4:5], 1, s[6:7]
	global_store_short v[4:5], v2, off
	v_add_u32_e32 v4, 0x1b020, v68
	v_mov_b32_e32 v5, v3
	v_lshl_add_u64 v[4:5], v[4:5], 1, s[6:7]
	global_store_short_d16_hi v[4:5], v2, off
	v_mul_f32_e32 v1, v1, v7
	v_add_u32_e32 v4, 0x1b040, v68
	v_mov_b32_e32 v5, v3
	v_mul_f32_e32 v2, v8, v7
	v_mul_f32_e32 v1, v73, v1
	v_lshl_add_u64 v[4:5], v[4:5], 1, s[6:7]
	v_mul_f32_e32 v2, v71, v2
	v_cvt_pk_bf16_f32 v1, v2, v1
	global_store_short v[4:5], v1, off
	v_add_u32_e32 v4, 0x1b060, v68
	v_mov_b32_e32 v5, v3
	v_lshl_add_u64 v[4:5], v[4:5], 1, s[6:7]
	global_store_short_d16_hi v[4:5], v1, off
